# P2/P6/P8: all sample-row tiles on the small-first half (two each) so the two halves' residual epilogues are offset by two tiles
# baseline (speedup 1.0000x reference)
; #define LAS __attribute__((address_space(3)))
;     __device__ __forceinline__ Pre pre4(int row, int col) const { const float* sb = (row < TP) ? srcP : srcS - (size_t)TP * DM; Pre p; p.s = NTL((const f32x4*)(sb + (size_t)row * DM + col)); return p; }
;     __device__ __forceinline__ Pre pre4(int row, int col) const { const size_t o = (size_t)row * DM + col; Pre p; p.g = NTL((const v2u*)(SG + o)); p.m = (v2u){0u, 0u}; if (MODE == 1) p.m = NTL((const v2u*)(MG + o)); return p; }
; __device__ __forceinline__ const float* kin(int k) { KArgs p = (KArgs)__builtin_amdgcn_kernarg_segment_ptr(); asm volatile("" : "+s"(p)); return p->in[k]; }
; #define REFRESH() do { int t_ = threadIdx.x; asm volatile("" : "+v"(t_)); F.tid = t_; F.lane = t_ & 63; F.wave = __builtin_amdgcn_readfirstlane(t_ >> 6); } while (0)
; template <class Epi>
; __device__ __forceinline__ void small_gemm(const Frame& F, const bf16* A, const bf16* Bt, int row_base, int K, const Epi E) {
;     constexpr int LDT = 136, BUF = 64 * LDT;
;     LAS bf16* As = (LAS bf16*)F.lds; LAS bf16* Bs = As + 2 * BUF;
;     const int tid = F.tid, lane = F.lane, w = F.wave, r = lane & 15, q = lane >> 4, prow = tid >> 3, pk = (tid & 7) * 8, ns = K / 128;
;     for (int u = F.vcu; u < 256; u += F.G) {
;         const int r0 = row_base + (u >> 4) * 64, c0 = (u & 15) * 64;
;         const bf16* ap = A + (size_t)(r0 + prow) * K + pk; const bf16* bp = Bt + (size_t)(c0 + prow) * K + pk;
;         f32x4 acc0 = {0.f, 0.f, 0.f, 0.f}, acc1 = {0.f, 0.f, 0.f, 0.f};
;         const typename Epi::Pre ep0 = E.pre4(r0 + 16 * (w & 3) + r, c0 + 32 * (w >> 2) + 4 * q), ep1 = E.pre4(r0 + 16 * (w & 3) + r, c0 + 32 * (w >> 2) + 16 + 4 * q);
; __global__ void __launch_bounds__(NWAVES * 64, 2) mk_fwd(Args args) {
;     ...
;       if ((blockIdx.x >> 3) & 1) { small_gemm(F, Hb, (const bf16*)(ws + WS_W2), TP, DFF, pg8::EpiRes<true>{kin(0), kin(1), out, XN, PARTP_, PARTS_, F.lds, kin(9)}); REFRESH(); pg8::gemm_phase<pg8::EpiRes<true>, pg8::StaticOrder, true, true>(F.lds, g, S, E); }
.LBB0_65:
	s_mov_b64 s[6:7], s[0:1]
	s_load_dwordx2 s[36:37], s[6:7], 0x0
	s_mov_b64 s[6:7], s[0:1]
	s_add_u32 s16, s22, 0x1b00000
	s_addc_u32 s17, s23, 0
	s_load_dwordx2 s[42:43], s[6:7], 0x8
	s_mov_b64 s[6:7], s[0:1]
	s_add_u32 s38, s22, 0xfd80000
	s_load_dwordx2 s[40:41], s[6:7], 0x48
	s_addc_u32 s39, s23, 0
	s_add_u32 s14, s22, 0xfdc0000
	s_addc_u32 s15, s23, 0
	s_bitcmp0_b32 s2, 3
	s_mov_b64 s[6:7], -1
	s_cbranch_scc1 .LBB0_187
	s_mov_b64 s[6:7], s[0:1]
	s_mov_b64 s[8:9], s[0:1]
	s_mov_b64 s[10:11], s[0:1]
	s_cmpk_gt_i32 s33, 0xff
	s_cbranch_scc1 .LBB0_77
	s_load_dwordx2 s[46:47], s[6:7], 0x0
	s_load_dwordx2 s[48:49], s[8:9], 0x8
	s_load_dwordx2 s[12:13], s[10:11], 0x48
	s_lshl_b32 s3, s50, 4
	s_ashr_i32 s8, s50, 2
	s_and_b32 s3, s3, 48
	s_lshl_b32 s19, s8, 5
	s_waitcnt lgkmcnt(0)
	s_add_u32 s34, s48, 0xfc000000
	s_addc_u32 s35, s49, -1
	v_ashrrev_i32_e32 v1, 3, v188
	v_lshlrev_b32_e32 v2, 4, v188
	s_movk_i32 s6, 0x110
	s_cmp_lg_u64 s[22:23], 0
	v_and_b32_e32 v2, 0x70, v2
	v_and_b32_e32 v4, 15, v189
	v_mov_b32_e32 v3, 0
	v_mul_lo_u32 v5, v1, s6
	s_cselect_b64 s[10:11], -1, 0
	s_lshl_b32 s44, s8, 8
	v_lshl_add_u64 v[18:19], s[28:29], 0, v[2:3]
	v_lshl_add_u64 v[20:21], s[16:17], 0, v[2:3]
	v_or_b32_e32 v30, s3, v4
	v_add3_u32 v31, 0, v2, v5
	v_or_b32_e32 v4, s19, v4
	v_add3_u32 v34, 0, v5, v2
	s_add_i32 s44, s44, 0
	s_lshl_b32 s3, s3, 2
	v_cndmask_b32_e64 v2, 0, 1, s[10:11]
	v_lshrrev_b32_e32 v3, 2, v189
	v_mul_u32_u24_e32 v6, 0x110, v30
	v_and_b32_e32 v7, 48, v189
	v_mul_lo_u32 v4, v4, s6
	s_add_i32 s44, s44, s3
	v_cmp_ne_u32_e64 s[10:11], 1, v2
	v_mbcnt_lo_u32_b32 v2, -1, 0
	s_mov_b32 s45, 0
	v_add3_u32 v32, 0, v6, v7
	v_add3_u32 v33, 0, v4, v7
	v_cmp_gt_u32_e64 s[6:7], 16, v189
	v_cmp_gt_i32_e64 s[8:9], 64, v188
	v_lshl_add_u32 v35, v189, 2, s44
	v_lshl_add_u32 v36, v188, 2, 0
	v_and_or_b32 v37, v3, 12, s19
	s_lshr_b32 s3, s2, 4
	s_lshl_b32 s3, s3, 3
	s_and_b32 s19, s2, 7
	s_or_b32 s3, s3, s19
	s_lshl_b32 s3, s3, 2
	s_movk_i32 s19, 0x200
	s_movk_i32 s48, 0x4000
	s_movk_i32 s49, 0x1600
	v_mov_b32_e32 v38, s35
	v_mov_b32_e32 v39, s47
	v_mov_b32_e32 v40, s34
	v_mov_b32_e32 v41, s46
	s_movk_i32 s50, 0x1000
	v_mbcnt_hi_u32_b32 v42, -1, v2
	s_lshr_b32 s51, s3, 2
	s_branch .LBB0_70

; template <class Epi>
; __device__ __forceinline__ void small_gemm(const Frame& F, const bf16* A, const bf16* Bt, int row_base, int K, const Epi E) {
;     ...
;     for (int u = F.vcu; u < 256; u += F.G) {
;         const int r0 = row_base + (u >> 4) * 64, c0 = (u & 15) * 64;
;         const bf16* ap = A + (size_t)(r0 + prow) * K + pk; const bf16* bp = Bt + (size_t)(c0 + prow) * K + pk;
.LBB0_69:
	s_addk_i32 s51, 0x80
	s_add_i32 s3, s3, s19
	s_cmpk_lt_i32 s51, 0x100
	s_cbranch_scc0 .LBB0_77

; __device__ __forceinline__ const float* kin(int k) { KArgs p = (KArgs)__builtin_amdgcn_kernarg_segment_ptr(); asm volatile("" : "+s"(p)); return p->in[k]; }
; #define REFRESH() do { int t_ = threadIdx.x; asm volatile("" : "+v"(t_)); F.tid = t_; F.lane = t_ & 63; F.wave = __builtin_amdgcn_readfirstlane(t_ >> 6); } while (0)
; template <class Epi>
; __device__ __forceinline__ void small_gemm(const Frame& F, const bf16* A, const bf16* Bt, int row_base, int K, const Epi E) {
;     ...
;     for (int u = F.vcu; u < 256; u += F.G) {
;         const int r0 = row_base + (u >> 4) * 64, c0 = (u & 15) * 64;
;         const bf16* ap = A + (size_t)(r0 + prow) * K + pk; const bf16* bp = Bt + (size_t)(c0 + prow) * K + pk;
; __global__ void __launch_bounds__(NWAVES * 64, 2) mk_fwd(Args args) {
;     ...
;       else { pg8::gemm_phase<pg8::EpiRes<true>, pg8::StaticOrder, true, true>(F.lds, g, S, E); REFRESH(); small_gemm(F, Hb, (const bf16*)(ws + WS_W2), TP, DFF, pg8::EpiRes<true>{kin(0), kin(1), out, XN, PARTP_, PARTS_, F.lds, kin(9)}); } }
.LBB0_297:
	v_mov_b32_e32 v1, v0
	s_mov_b64 s[6:7], s[0:1]
	v_readfirstlane_b32 s19, v1
	s_mov_b64 s[8:9], s[0:1]
	s_mov_b64 s[10:11], s[0:1]
	s_cmp_eq_u32 s33, s33
	s_cbranch_scc1 .LBB0_308
	s_waitcnt lgkmcnt(0)
	s_load_dwordx2 s[42:43], s[6:7], 0x0
	s_load_dwordx2 s[38:39], s[8:9], 0x8
	s_load_dwordx2 s[12:13], s[10:11], 0x48
	v_lshlrev_b32_e32 v2, 4, v1
	v_and_b32_e32 v2, 0x70, v2
	v_mov_b32_e32 v3, 0
	s_lshr_b32 s3, s19, 2
	v_lshl_add_u64 v[20:21], s[16:17], 0, v[2:3]
	s_and_b32 s16, s3, 48
	s_ashr_i32 s3, s19, 3
	s_andn2_b32 s3, s3, 31
	s_waitcnt lgkmcnt(0)
	s_add_u32 s17, s38, 0xfc000000
	s_addc_u32 s34, s39, -1
	v_ashrrev_i32_e32 v30, 3, v1
	v_lshl_add_u64 v[18:19], s[28:29], 0, v[2:3]
	v_lshrrev_b32_e32 v3, 2, v1
	s_movk_i32 s6, 0x110
	s_cmp_lg_u64 s[22:23], 0
	v_and_b32_e32 v5, 15, v1
	v_and_b32_e32 v32, 12, v3
	v_mul_lo_u32 v3, v30, s6
	s_cselect_b64 s[10:11], -1, 0
	s_and_b32 s19, s19, 0xffffff00
	v_or_b32_e32 v31, s16, v5
	v_add3_u32 v33, 0, v2, v3
	v_or_b32_e32 v5, s3, v5
	v_add3_u32 v36, 0, v3, v2
	s_add_i32 s19, s19, 0
	s_lshl_b32 s16, s16, 2
	v_cndmask_b32_e64 v2, 0, 1, s[10:11]
	v_and_b32_e32 v4, 63, v1
	v_mul_u32_u24_e32 v6, 0x110, v31
	v_and_b32_e32 v7, 48, v1
	v_mul_lo_u32 v5, v5, s6
	s_add_i32 s19, s19, s16
	v_cmp_ne_u32_e64 s[10:11], 1, v2
	v_mbcnt_lo_u32_b32 v2, -1, 0
	s_mov_b32 s37, 0
	v_add3_u32 v34, 0, v6, v7
	v_add3_u32 v35, 0, v5, v7
	v_cmp_gt_u32_e64 s[6:7], 16, v4
	v_cmp_gt_i32_e64 s[8:9], 64, v1
	v_lshl_add_u32 v37, v4, 2, s19
	v_lshl_add_u32 v38, v1, 2, 0
	s_lshl_b32 s19, s33, 2
	s_lshl_b32 s38, s18, 2
	s_movk_i32 s39, 0x4000
	s_movk_i32 s40, 0x1600
	v_mov_b32_e32 v39, s34
	v_mov_b32_e32 v40, s43
	v_mov_b32_e32 v41, s17
	v_mov_b32_e32 v42, s42
	s_movk_i32 s41, 0x1000
	v_mbcnt_hi_u32_b32 v43, -1, v2
	s_mov_b32 s42, s33
	s_branch .LBB0_301

; #define LAS __attribute__((address_space(3)))
;     __device__ __forceinline__ Pre pre4(int row, int col) const { const float* sb = (row < TP) ? srcP : srcS - (size_t)TP * DM; Pre p; p.s = NTL((const f32x4*)(sb + (size_t)row * DM + col)); return p; }
;     __device__ __forceinline__ Pre pre4(int row, int col) const { const size_t o = (size_t)row * DM + col; Pre p; p.g = NTL((const v2u*)(SG + o)); p.m = (v2u){0u, 0u}; if (MODE == 1) p.m = NTL((const v2u*)(MG + o)); return p; }
; __device__ __forceinline__ const float* kin(int k) { KArgs p = (KArgs)__builtin_amdgcn_kernarg_segment_ptr(); asm volatile("" : "+s"(p)); return p->in[k]; }
; #define REFRESH() do { int t_ = threadIdx.x; asm volatile("" : "+v"(t_)); F.tid = t_; F.lane = t_ & 63; F.wave = __builtin_amdgcn_readfirstlane(t_ >> 6); } while (0)
; template <class Epi>
; __device__ __forceinline__ void small_gemm(const Frame& F, const bf16* A, const bf16* Bt, int row_base, int K, const Epi E) {
;     constexpr int LDT = 136, BUF = 64 * LDT;
;     LAS bf16* As = (LAS bf16*)F.lds; LAS bf16* Bs = As + 2 * BUF;
;     const int tid = F.tid, lane = F.lane, w = F.wave, r = lane & 15, q = lane >> 4, prow = tid >> 3, pk = (tid & 7) * 8, ns = K / 128;
;     for (int u = F.vcu; u < 256; u += F.G) {
;         const int r0 = row_base + (u >> 4) * 64, c0 = (u & 15) * 64;
;         const bf16* ap = A + (size_t)(r0 + prow) * K + pk; const bf16* bp = Bt + (size_t)(c0 + prow) * K + pk;
;         f32x4 acc0 = {0.f, 0.f, 0.f, 0.f}, acc1 = {0.f, 0.f, 0.f, 0.f};
;         const typename Epi::Pre ep0 = E.pre4(r0 + 16 * (w & 3) + r, c0 + 32 * (w >> 2) + 4 * q), ep1 = E.pre4(r0 + 16 * (w & 3) + r, c0 + 32 * (w >> 2) + 16 + 4 * q);
; __global__ void __launch_bounds__(NWAVES * 64, 2) mk_fwd(Args args) {
;     ...
;       if ((blockIdx.x >> 3) & 1) { small_gemm(F, (const bf16*)(ws + WS_MG), (const bf16*)(ws + WS_WO), TP, DM, pg8::EpiRes<false>{out, out + (size_t)TP * DM, out, XN, PARTP_, PARTS_, F.lds, kin(16)}); REFRESH(); pg8::gemm_phase<pg8::EpiRes<false>, pg8::StaticOrder, true, true>(F.lds, g, S, E); }
.LBB0_1300:
	s_add_u32 s16, s22, 0xdb80000
	s_addc_u32 s17, s23, 0
	s_add_u32 s36, s22, 0xe00000
	s_addc_u32 s37, s23, 0
	s_mov_b64 s[6:7], s[0:1]
	s_add_u32 s38, s22, 0xfd80000
	s_load_dwordx2 s[40:41], s[6:7], 0x80
	s_addc_u32 s39, s23, 0
	s_add_u32 s14, s22, 0xfdc0000
	s_addc_u32 s15, s23, 0
	s_bitcmp0_b32 s2, 3
	s_mov_b64 s[6:7], -1
	s_cbranch_scc1 .LBB0_1401
	s_mov_b64 s[6:7], s[0:1]
	s_cmpk_gt_i32 s33, 0xff
	s_cbranch_scc1 .LBB0_1312
	s_lshl_b32 s3, s50, 4
	s_ashr_i32 s8, s50, 2
	s_and_b32 s3, s3, 48
	s_lshl_b32 s19, s8, 5
	s_load_dwordx2 s[12:13], s[6:7], 0x80
	v_ashrrev_i32_e32 v1, 3, v188
	v_lshlrev_b32_e32 v2, 4, v188
	s_movk_i32 s6, 0x110
	s_cmp_lg_u64 s[22:23], 0
	v_and_b32_e32 v2, 0x70, v2
	v_and_b32_e32 v4, 15, v189
	v_mov_b32_e32 v3, 0
	v_mul_lo_u32 v5, v1, s6
	s_cselect_b64 s[10:11], -1, 0
	s_lshl_b32 s34, s8, 8
	s_waitcnt vmcnt(7)
	v_lshl_add_u64 v[18:19], s[16:17], 0, v[2:3]
	v_lshl_add_u64 v[20:21], s[36:37], 0, v[2:3]
	v_or_b32_e32 v28, s3, v4
	v_add3_u32 v29, 0, v2, v5
	v_or_b32_e32 v4, s19, v4
	v_add3_u32 v32, 0, v5, v2
	s_add_i32 s34, s34, 0
	s_lshl_b32 s3, s3, 2
	v_cndmask_b32_e64 v2, 0, 1, s[10:11]
	v_lshrrev_b32_e32 v3, 2, v189
	v_mul_u32_u24_e32 v6, 0x110, v28
	v_and_b32_e32 v7, 48, v189
	v_mul_lo_u32 v4, v4, s6
	s_add_i32 s34, s34, s3
	v_cmp_ne_u32_e64 s[10:11], 1, v2
	v_mbcnt_lo_u32_b32 v2, -1, 0
	s_mov_b32 s43, 0
	v_add3_u32 v30, 0, v6, v7
	v_add3_u32 v31, 0, v4, v7
	v_cmp_gt_u32_e64 s[6:7], 16, v189
	v_cmp_gt_i32_e64 s[8:9], 64, v188
	v_lshl_add_u32 v33, v189, 2, s34
	s_waitcnt vmcnt(4)
	v_lshl_add_u32 v34, v188, 2, 0
	v_and_or_b32 v35, v3, 12, s19
	s_lshr_b32 s3, s2, 4
	s_lshl_b32 s3, s3, 3
	s_and_b32 s19, s2, 7
	s_or_b32 s3, s3, s19
	s_lshl_b32 s3, s3, 2
	s_movk_i32 s19, 0x200
	v_mbcnt_hi_u32_b32 v36, -1, v2
	s_lshr_b32 s46, s3, 2
	s_branch .LBB0_1305

; template <class Epi>
; __device__ __forceinline__ void small_gemm(const Frame& F, const bf16* A, const bf16* Bt, int row_base, int K, const Epi E) {
;     ...
;     for (int u = F.vcu; u < 256; u += F.G) {
;         const int r0 = row_base + (u >> 4) * 64, c0 = (u & 15) * 64;
;         const bf16* ap = A + (size_t)(r0 + prow) * K + pk; const bf16* bp = Bt + (size_t)(c0 + prow) * K + pk;
.LBB0_1304:
	s_addk_i32 s46, 0x80
	s_add_i32 s3, s3, s19
	s_cmpk_lt_i32 s46, 0x100
	s_cbranch_scc0 .LBB0_1312

; __device__ __forceinline__ const float* kin(int k) { KArgs p = (KArgs)__builtin_amdgcn_kernarg_segment_ptr(); asm volatile("" : "+s"(p)); return p->in[k]; }
; #define REFRESH() do { int t_ = threadIdx.x; asm volatile("" : "+v"(t_)); F.tid = t_; F.lane = t_ & 63; F.wave = __builtin_amdgcn_readfirstlane(t_ >> 6); } while (0)
; template <class Epi>
; __device__ __forceinline__ void small_gemm(const Frame& F, const bf16* A, const bf16* Bt, int row_base, int K, const Epi E) {
;     ...
;     for (int u = F.vcu; u < 256; u += F.G) {
;         const int r0 = row_base + (u >> 4) * 64, c0 = (u & 15) * 64;
;         const bf16* ap = A + (size_t)(r0 + prow) * K + pk; const bf16* bp = Bt + (size_t)(c0 + prow) * K + pk;
; __global__ void __launch_bounds__(NWAVES * 64, 2) mk_fwd(Args args) {
;     ...
;       else { pg8::gemm_phase<pg8::EpiRes<false>, pg8::StaticOrder, true, true>(F.lds, g, S, E); REFRESH(); small_gemm(F, (const bf16*)(ws + WS_MG), (const bf16*)(ws + WS_WO), TP, DM, pg8::EpiRes<false>{out, out + (size_t)TP * DM, out, XN, PARTP_, PARTS_, F.lds, kin(16)}); } }
.LBB0_1490:
	v_mov_b32_e32 v1, v0
	s_mov_b64 s[6:7], s[0:1]
	v_readfirstlane_b32 s8, v1
	s_cmp_eq_u32 s33, s33
	s_cbranch_scc1 .LBB0_1501
	v_lshlrev_b32_e32 v2, 4, v1
	v_and_b32_e32 v2, 0x70, v2
	s_waitcnt lgkmcnt(0)
	v_mov_b32_e32 v3, 0
	s_lshr_b32 s3, s8, 2
	s_waitcnt vmcnt(7)
	v_lshl_add_u64 v[18:19], s[16:17], 0, v[2:3]
	s_and_b32 s16, s3, 48
	s_ashr_i32 s3, s8, 3
	s_andn2_b32 s3, s3, 31
	s_load_dwordx2 s[12:13], s[6:7], 0x80
	v_ashrrev_i32_e32 v28, 3, v1
	v_lshl_add_u64 v[20:21], s[36:37], 0, v[2:3]
	v_lshrrev_b32_e32 v3, 2, v1
	s_movk_i32 s6, 0x110
	s_cmp_lg_u64 s[22:23], 0
	v_and_b32_e32 v5, 15, v1
	v_and_b32_e32 v30, 12, v3
	v_mul_lo_u32 v3, v28, s6
	s_cselect_b64 s[10:11], -1, 0
	s_and_b32 s17, s8, 0xffffff00
	v_or_b32_e32 v29, s16, v5
	v_add3_u32 v31, 0, v2, v3
	v_or_b32_e32 v5, s3, v5
	s_waitcnt vmcnt(4)
	v_add3_u32 v34, 0, v3, v2
	s_add_i32 s17, s17, 0
	s_lshl_b32 s16, s16, 2
	v_cndmask_b32_e64 v2, 0, 1, s[10:11]
	v_and_b32_e32 v4, 63, v1
	v_mul_u32_u24_e32 v6, 0x110, v29
	v_and_b32_e32 v7, 48, v1
	v_mul_lo_u32 v5, v5, s6
	s_add_i32 s17, s17, s16
	v_cmp_ne_u32_e64 s[10:11], 1, v2
	v_mbcnt_lo_u32_b32 v2, -1, 0
	s_mov_b32 s39, 0
	v_add3_u32 v32, 0, v6, v7
	v_add3_u32 v33, 0, v5, v7
	v_cmp_gt_u32_e64 s[6:7], 16, v4
	v_cmp_gt_i32_e64 s[8:9], 64, v1
	v_lshl_add_u32 v35, v4, 2, s17
	v_lshl_add_u32 v36, v1, 2, 0
	s_lshl_b32 s19, s33, 2
	s_lshl_b32 s36, s18, 2
	v_mbcnt_hi_u32_b32 v37, -1, v2
	s_mov_b32 s37, s33
	s_branch .LBB0_1494

; #define LDSBAR() do { asm volatile("s_waitcnt lgkmcnt(0)" ::: "memory"); __builtin_amdgcn_s_barrier(); asm volatile("" ::: "memory"); } while (0)
;     __device__ __forceinline__ Pre pre4(int row, int col) const { const float* sb = (row < TP) ? srcP : srcS - (size_t)TP * DM; Pre p; p.s = NTL((const f32x4*)(sb + (size_t)row * DM + col)); return p; }
;     __device__ __forceinline__ Pre pre4(int row, int col) const { const size_t o = (size_t)row * DM + col; Pre p; p.g = NTL((const v2u*)(SG + o)); p.m = (v2u){0u, 0u}; if (MODE == 1) p.m = NTL((const v2u*)(MG + o)); return p; }
; template <class Epi>
; __device__ __forceinline__ void small_gemm(const Frame& F, const bf16* A, const bf16* Bt, int row_base, int K, const Epi E) {
;     ...
;     const int tid = F.tid, lane = F.lane, w = F.wave, r = lane & 15, q = lane >> 4, prow = tid >> 3, pk = (tid & 7) * 8, ns = K / 128;
;     for (int u = F.vcu; u < 256; u += F.G) {
;         const int r0 = row_base + (u >> 4) * 64, c0 = (u & 15) * 64;
;         const bf16* ap = A + (size_t)(r0 + prow) * K + pk; const bf16* bp = Bt + (size_t)(c0 + prow) * K + pk;
;         f32x4 acc0 = {0.f, 0.f, 0.f, 0.f}, acc1 = {0.f, 0.f, 0.f, 0.f};
;         const typename Epi::Pre ep0 = E.pre4(r0 + 16 * (w & 3) + r, c0 + 32 * (w >> 2) + 4 * q), ep1 = E.pre4(r0 + 16 * (w & 3) + r, c0 + 32 * (w >> 2) + 16 + 4 * q);
;     ...
;         SgPre R0, R1, R2, R3;
;         SG_LOAD(R0, 0); SG_LOAD(R1, 1); SG_LOAD(R2, 2);
;         SG_STORE(R0, 0); LDSBAR();
;         for (int s = 0; s < ns; s += 4) {
;             SG_LOAD(R3, s + 3); SG_COMP(0); if (s + 1 < ns) SG_STORE(R1, 1); LDSBAR(); if (s + 1 >= ns) break;
;             SG_LOAD(R0, s + 4); SG_COMP(1); if (s + 2 < ns) SG_STORE(R2, 0); LDSBAR(); if (s + 2 >= ns) break;
;             SG_LOAD(R1, s + 5); SG_COMP(0); if (s + 3 < ns) SG_STORE(R3, 1); LDSBAR(); if (s + 3 >= ns) break;
;             SG_LOAD(R2, s + 6); SG_COMP(1); if (s + 4 < ns) SG_STORE(R0, 0); LDSBAR();
; __global__ void __launch_bounds__(NWAVES * 64, 2) mk_fwd(Args args) {
;     ...
;       if ((blockIdx.x >> 3) & 1) { small_gemm(F, Hb, (const bf16*)(ws + WS_W2), TP, DFF, pg8::EpiRes<true>{out, out + (size_t)TP * DM, out, nullptr, nullptr, nullptr, F.lds, nullptr}); REFRESH(); pg8::gemm_phase<pg8::EpiRes<true>, pg8::StaticOrder, true, true>(F.lds, g, S, E); }
.LBB0_1873:
	s_or_b64 exec, exec, s[6:7]
	s_add_u32 s10, s22, 0x1b00000
	s_waitcnt lgkmcnt(0)
	v_mov_b32_e32 v2, v0
	s_addc_u32 s11, s23, 0
	s_barrier
	s_bitcmp0_b32 s2, 3
	v_readfirstlane_b32 s3, v2
	s_mov_b64 s[6:7], -1
	s_cbranch_scc1 .LBB0_1906
	s_cmpk_gt_i32 s33, 0xff
	s_cbranch_scc1 .LBB0_1877
	v_lshlrev_b32_e32 v3, 4, v2
	s_lshr_b32 s6, s3, 2
	s_ashr_i32 s3, s3, 3
	v_ashrrev_i32_e32 v38, 3, v2
	v_and_b32_e32 v4, 0x70, v3
	v_bfe_u32 v3, v2, 4, 2
	v_and_b32_e32 v2, 15, v2
	s_andn2_b32 s3, s3, 31
	v_mov_b32_e32 v5, 0
	v_and_or_b32 v39, s6, 48, v2
	s_movk_i32 s6, 0x110
	v_or_b32_e32 v2, s3, v2
	v_lshl_add_u64 v[26:27], s[28:29], 0, v[4:5]
	v_lshl_add_u64 v[28:29], s[10:11], 0, v[4:5]
	v_lshlrev_b32_e32 v40, 2, v3
	v_mul_lo_u32 v5, v38, s6
	v_mul_u32_u24_e32 v6, 0x110, v39
	v_lshlrev_b32_e32 v3, 4, v3
	v_mul_lo_u32 v2, v2, s6
	v_add3_u32 v41, 0, v4, v5
	v_add3_u32 v42, 0, v6, v3
	v_add3_u32 v43, 0, v2, v3
	v_add3_u32 v44, 0, v5, v4
	s_lshr_b32 s8, s2, 4
	s_lshl_b32 s8, s8, 3
	s_and_b32 s6, s2, 7
	s_or_b32 s8, s8, s6
	s_lshl_b32 s6, s8, 6
	s_movk_i32 s7, 0x2000
	s_lshl_b32 s8, s8, 2
	s_movk_i32 s9, 0x200
	s_movk_i32 s12, 0x1600
	s_movk_i32 s13, 0x1000
	s_lshr_b32 s14, s8, 2
.LBB0_1876:
	s_and_b32 s15, s8, 0xffffffc0
	s_and_b32 s16, s6, 0x3c0
	s_addk_i32 s15, 0x4000
	v_add_u32_e32 v2, s16, v38
	s_add_i32 s19, s16, s3
	v_add_u32_e32 v3, s15, v38
	v_mad_i64_i32 v[32:33], s[16:17], v2, s12, v[28:29]
	v_mad_i64_i32 v[34:35], s[16:17], v3, s12, v[26:27]
	global_load_dwordx4 v[10:13], v[32:33], off
	global_load_dwordx4 v[14:17], v[32:33], off offset:128
	global_load_dwordx4 v[18:21], v[32:33], off offset:256
	global_load_dwordx4 v[22:25], v[32:33], off offset:384
	global_load_dwordx4 v[46:49], v[32:33], off offset:640
	global_load_dwordx4 v[50:53], v[32:33], off offset:512
	global_load_dwordx4 v[54:57], v[34:35], off
	global_load_dwordx4 v[58:61], v[34:35], off offset:128
	global_load_dwordx4 v[62:65], v[34:35], off offset:256
	global_load_dwordx4 v[66:69], v[34:35], off offset:384
	global_load_dwordx4 v[70:73], v[34:35], off offset:512
	global_load_dwordx4 v[74:77], v[34:35], off offset:640
	v_or_b32_e32 v2, s15, v39
	v_ashrrev_i32_e32 v3, 31, v2
	v_or_b32_e32 v4, s19, v40
	v_lshlrev_b64 v[2:3], 12, v[2:3]
	v_ashrrev_i32_e32 v5, 31, v4
	v_lshl_add_u64 v[2:3], s[20:21], 0, v[2:3]
	v_lshl_add_u64 v[30:31], v[4:5], 2, v[2:3]
	global_load_dwordx4 v[6:9], v[30:31], off
	global_load_dwordx4 v[2:5], v[30:31], off offset:64
	v_add_co_u32_e32 v36, vcc, s13, v32
	s_addk_i32 s14, 0x80
	s_nop 0
	v_addc_co_u32_e32 v37, vcc, 0, v33, vcc
	s_add_i32 s6, s6, s7
	s_add_i32 s8, s8, s9
	s_cmpk_lt_i32 s14, 0x100
	s_waitcnt vmcnt(13)
	ds_write_b128 v41, v[10:13] offset:34816
	s_waitcnt vmcnt(12)
	ds_write_b128 v41, v[14:17] offset:34944
	s_waitcnt vmcnt(7)
	ds_write_b128 v41, v[54:57]
	s_waitcnt vmcnt(6)
	ds_write_b128 v41, v[58:61] offset:128
	s_waitcnt lgkmcnt(0)
	s_barrier
	ds_read_b128 v[10:13], v43 offset:34816
	ds_read_b128 v[14:17], v43 offset:39168
	ds_read_b128 v[54:57], v42
	ds_read_b128 v[58:61], v42 offset:64
	ds_read_b128 v[78:81], v43 offset:34880
	global_load_dwordx4 v[82:85], v[34:35], off offset:768
	global_load_dwordx4 v[86:89], v[34:35], off offset:896
	ds_read_b128 v[90:93], v43 offset:39232
	s_waitcnt lgkmcnt(3)
	v_mfma_f32_16x16x32_bf16 v[10:13], v[10:13], v[54:57], 0
	v_mfma_f32_16x16x32_bf16 v[14:17], v[14:17], v[54:57], 0
	global_load_dwordx4 v[54:57], v[32:33], off offset:768
	global_load_dwordx4 v[94:97], v[32:33], off offset:896
	ds_read_b128 v[98:101], v43 offset:34944
	s_waitcnt lgkmcnt(2)
	v_mfma_f32_16x16x32_bf16 v[10:13], v[78:81], v[58:61], v[10:13]
	ds_read_b128 v[78:81], v43 offset:39296
	ds_read_b128 v[102:105], v42 offset:128
	ds_read_b128 v[106:109], v42 offset:192
	s_waitcnt lgkmcnt(4)
	v_mfma_f32_16x16x32_bf16 v[14:17], v[90:93], v[58:61], v[14:17]
	ds_read_b128 v[58:61], v43 offset:35008
	ds_read_b128 v[90:93], v43 offset:39360
	s_waitcnt vmcnt(9)
	ds_write_b128 v44, v[62:65] offset:17408
	s_waitcnt vmcnt(8)
	ds_write_b128 v44, v[66:69] offset:17536
	ds_write_b128 v44, v[18:21] offset:52224
	ds_write_b128 v44, v[22:25] offset:52352
	s_waitcnt lgkmcnt(7)
	v_mfma_f32_16x16x32_bf16 v[10:13], v[98:101], v[102:105], v[10:13]
	s_waitcnt lgkmcnt(0)
	s_barrier
	v_mfma_f32_16x16x32_bf16 v[14:17], v[78:81], v[102:105], v[14:17]
	ds_read_b128 v[18:21], v43 offset:52224
	ds_read_b128 v[22:25], v43 offset:56576
	s_waitcnt lgkmcnt(7)
	v_mfma_f32_16x16x32_bf16 v[10:13], v[58:61], v[106:109], v[10:13]
	ds_read_b128 v[58:61], v42 offset:17408
	ds_read_b128 v[62:65], v42 offset:17472
	ds_read_b128 v[66:69], v43 offset:52288
	s_waitcnt lgkmcnt(9)
	v_mfma_f32_16x16x32_bf16 v[14:17], v[90:93], v[106:109], v[14:17]
	s_waitcnt lgkmcnt(2)
	v_mfma_f32_16x16x32_bf16 v[10:13], v[18:21], v[58:61], v[10:13]
	global_load_dwordx4 v[18:21], v[34:35], off offset:1024
	global_load_dwordx4 v[78:81], v[34:35], off offset:1152
	ds_read_b128 v[90:93], v43 offset:56640
	v_mfma_f32_16x16x32_bf16 v[14:17], v[22:25], v[58:61], v[14:17]
	global_load_dwordx4 v[22:25], v[32:33], off offset:1024
	global_load_dwordx4 v[58:61], v[32:33], off offset:1152
	ds_read_b128 v[98:101], v43 offset:52352
	s_waitcnt lgkmcnt(2)
	v_mfma_f32_16x16x32_bf16 v[10:13], v[66:69], v[62:65], v[10:13]
	ds_read_b128 v[66:69], v43 offset:56704
	ds_read_b128 v[102:105], v42 offset:17536
	ds_read_b128 v[106:109], v42 offset:17600
	s_waitcnt lgkmcnt(4)
	v_mfma_f32_16x16x32_bf16 v[14:17], v[90:93], v[62:65], v[14:17]
	ds_read_b128 v[62:65], v43 offset:52416
	ds_read_b128 v[90:93], v43 offset:56768
	s_waitcnt vmcnt(11)
	ds_write_b128 v41, v[70:73]
	s_waitcnt vmcnt(10)
	ds_write_b128 v41, v[74:77] offset:128
	ds_write_b128 v41, v[50:53] offset:34816
	ds_write_b128 v41, v[46:49] offset:34944
	s_waitcnt lgkmcnt(0)
	s_barrier
; #define LDSBAR() do { asm volatile("s_waitcnt lgkmcnt(0)" ::: "memory"); __builtin_amdgcn_s_barrier(); asm volatile("" ::: "memory"); } while (0)
; #define SG_LOAD(R, s_) do { if ((s_) < ns) { R.a0 = NTL((const GAS v4u*)(ap + (s_) * 128)); R.a1 = NTL((const GAS v4u*)(ap + (s_) * 128 + 64)); R.b0 = NTL((const GAS v4u*)(bp + (s_) * 128)); R.b1 = NTL((const GAS v4u*)(bp + (s_) * 128 + 64)); } } while (0)
; #define SG_STORE(R, b_) do { *(LAS v4u*)(As + (b_) * BUF + prow * LDT + pk) = R.a0; *(LAS v4u*)(As + (b_) * BUF + prow * LDT + pk + 64) = R.a1; *(LAS v4u*)(Bs + (b_) * BUF + prow * LDT + pk) = R.b0; *(LAS v4u*)(Bs + (b_) * BUF + prow * LDT + pk + 64) = R.b1; } while (0)
; template <class Epi>
; __device__ __forceinline__ void small_gemm(const Frame& F, const bf16* A, const bf16* Bt, int row_base, int K, const Epi E) {
;     ...
;         SgPre R0, R1, R2, R3;
;         SG_LOAD(R0, 0); SG_LOAD(R1, 1); SG_LOAD(R2, 2);
;         SG_STORE(R0, 0); LDSBAR();
;         for (int s = 0; s < ns; s += 4) {
;             SG_LOAD(R3, s + 3); SG_COMP(0); if (s + 1 < ns) SG_STORE(R1, 1); LDSBAR(); if (s + 1 >= ns) break;
;             SG_LOAD(R0, s + 4); SG_COMP(1); if (s + 2 < ns) SG_STORE(R2, 0); LDSBAR(); if (s + 2 >= ns) break;
;             SG_LOAD(R1, s + 5); SG_COMP(0); if (s + 3 < ns) SG_STORE(R3, 1); LDSBAR(); if (s + 3 >= ns) break;
;             SG_LOAD(R2, s + 6); SG_COMP(1); if (s + 4 < ns) SG_STORE(R0, 0); LDSBAR();
	ds_read_b128 v[46:49], v43 offset:34816
	s_waitcnt lgkmcnt(8)
	v_mfma_f32_16x16x32_bf16 v[10:13], v[98:101], v[102:105], v[10:13]
	v_mfma_f32_16x16x32_bf16 v[14:17], v[66:69], v[102:105], v[14:17]
	s_waitcnt lgkmcnt(6)
	v_mfma_f32_16x16x32_bf16 v[10:13], v[62:65], v[106:109], v[10:13]
	ds_read_b128 v[50:53], v42
	ds_read_b128 v[62:65], v42 offset:64
	ds_read_b128 v[66:69], v43 offset:34880
	s_waitcnt lgkmcnt(8)
	v_mfma_f32_16x16x32_bf16 v[14:17], v[90:93], v[106:109], v[14:17]
	s_waitcnt lgkmcnt(2)
	v_mfma_f32_16x16x32_bf16 v[10:13], v[46:49], v[50:53], v[10:13]
	ds_read_b128 v[46:49], v43 offset:39168
	ds_read_b128 v[70:73], v43 offset:39232
	s_waitcnt lgkmcnt(1)
	v_mfma_f32_16x16x32_bf16 v[14:17], v[46:49], v[50:53], v[14:17]
	ds_read_b128 v[46:49], v43 offset:34944
	v_mfma_f32_16x16x32_bf16 v[10:13], v[66:69], v[62:65], v[10:13]
	s_waitcnt lgkmcnt(1)
	v_mfma_f32_16x16x32_bf16 v[14:17], v[70:73], v[62:65], v[14:17]
	ds_read_b128 v[50:53], v42 offset:128
	ds_read_b128 v[62:65], v42 offset:192
	ds_read_b128 v[66:69], v43 offset:35008
	s_waitcnt lgkmcnt(2)
	v_mfma_f32_16x16x32_bf16 v[10:13], v[46:49], v[50:53], v[10:13]
	ds_read_b128 v[46:49], v43 offset:39296
	ds_read_b128 v[70:73], v43 offset:39360
	s_waitcnt lgkmcnt(1)
	v_mfma_f32_16x16x32_bf16 v[14:17], v[46:49], v[50:53], v[14:17]
	global_load_dwordx4 v[46:49], v[34:35], off offset:1280
	global_load_dwordx4 v[50:53], v[34:35], off offset:1408
	global_load_dwordx4 v[74:77], v[32:33], off offset:1280
	v_mfma_f32_16x16x32_bf16 v[10:13], v[66:69], v[62:65], v[10:13]
	global_load_dwordx4 v[66:69], v[32:33], off offset:1408
	s_waitcnt vmcnt(11)
	ds_write_b128 v44, v[82:85] offset:17408
	s_waitcnt vmcnt(10)
	ds_write_b128 v44, v[86:89] offset:17536
	s_waitcnt vmcnt(9)
	ds_write_b128 v44, v[54:57] offset:52224
	s_waitcnt vmcnt(8)
	ds_write_b128 v44, v[94:97] offset:52352
	s_waitcnt lgkmcnt(0)
	s_barrier
	s_waitcnt lgkmcnt(4)
	v_mfma_f32_16x16x32_bf16 v[14:17], v[70:73], v[62:65], v[14:17]
	ds_read_b128 v[54:57], v43 offset:52224
	ds_read_b128 v[62:65], v43 offset:56576
	ds_read_b128 v[70:73], v42 offset:17408
	ds_read_b128 v[82:85], v42 offset:17472
	ds_read_b128 v[86:89], v43 offset:52288
	s_waitcnt lgkmcnt(2)
	v_mfma_f32_16x16x32_bf16 v[10:13], v[54:57], v[70:73], v[10:13]
	global_load_dwordx4 v[54:57], v[34:35], off offset:1536
	global_load_dwordx4 v[90:93], v[34:35], off offset:1664
	ds_read_b128 v[94:97], v43 offset:56640
	v_mfma_f32_16x16x32_bf16 v[14:17], v[62:65], v[70:73], v[14:17]
	global_load_dwordx4 v[62:65], v[32:33], off offset:1536
	global_load_dwordx4 v[70:73], v[32:33], off offset:1664
	ds_read_b128 v[98:101], v43 offset:52352
	s_waitcnt lgkmcnt(2)
	v_mfma_f32_16x16x32_bf16 v[10:13], v[86:89], v[82:85], v[10:13]
	ds_read_b128 v[86:89], v43 offset:56704
	ds_read_b128 v[102:105], v42 offset:17536
	ds_read_b128 v[106:109], v42 offset:17600
	s_waitcnt lgkmcnt(4)
	v_mfma_f32_16x16x32_bf16 v[14:17], v[94:97], v[82:85], v[14:17]
	ds_read_b128 v[82:85], v43 offset:52416
	ds_read_b128 v[94:97], v43 offset:56768
	s_waitcnt vmcnt(11)
	ds_write_b128 v41, v[18:21]
	s_waitcnt vmcnt(10)
	ds_write_b128 v41, v[78:81] offset:128
	s_waitcnt vmcnt(9)
	ds_write_b128 v41, v[22:25] offset:34816
	s_waitcnt vmcnt(8)
	ds_write_b128 v41, v[58:61] offset:34944
	s_waitcnt lgkmcnt(7)
	v_mfma_f32_16x16x32_bf16 v[10:13], v[98:101], v[102:105], v[10:13]
	s_waitcnt lgkmcnt(0)
	s_barrier
	v_mfma_f32_16x16x32_bf16 v[14:17], v[86:89], v[102:105], v[14:17]
	ds_read_b128 v[18:21], v43 offset:34816
	ds_read_b128 v[22:25], v43 offset:39168
	s_waitcnt lgkmcnt(7)
	v_mfma_f32_16x16x32_bf16 v[10:13], v[82:85], v[106:109], v[10:13]
	ds_read_b128 v[58:61], v42
	ds_read_b128 v[78:81], v42 offset:64
	ds_read_b128 v[82:85], v43 offset:34880
	s_waitcnt lgkmcnt(9)
	v_mfma_f32_16x16x32_bf16 v[14:17], v[94:97], v[106:109], v[14:17]
	global_load_dwordx4 v[86:89], v[34:35], off offset:1792
	global_load_dwordx4 v[94:97], v[34:35], off offset:1920
	s_waitcnt lgkmcnt(2)
	v_mfma_f32_16x16x32_bf16 v[10:13], v[18:21], v[58:61], v[10:13]
	ds_read_b128 v[18:21], v43 offset:39232
	v_mfma_f32_16x16x32_bf16 v[14:17], v[22:25], v[58:61], v[14:17]
	global_load_dwordx4 v[58:61], v[32:33], off offset:1792
	global_load_dwordx4 v[98:101], v[32:33], off offset:1920
	ds_read_b128 v[22:25], v43 offset:34944
	s_waitcnt lgkmcnt(2)
	v_mfma_f32_16x16x32_bf16 v[10:13], v[82:85], v[78:81], v[10:13]
	ds_read_b128 v[82:85], v43 offset:39296
	ds_read_b128 v[102:105], v42 offset:128
	ds_read_b128 v[106:109], v42 offset:192
	s_waitcnt lgkmcnt(4)
	v_mfma_f32_16x16x32_bf16 v[14:17], v[18:21], v[78:81], v[14:17]
	ds_read_b128 v[18:21], v43 offset:35008
	ds_read_b128 v[78:81], v43 offset:39360
	s_waitcnt vmcnt(11)
	ds_write_b128 v44, v[46:49] offset:17408
	s_waitcnt lgkmcnt(4)
	v_mfma_f32_16x16x32_bf16 v[10:13], v[22:25], v[102:105], v[10:13]
	s_waitcnt vmcnt(10)
	ds_write_b128 v44, v[50:53] offset:17536
	s_waitcnt vmcnt(9)
	ds_write_b128 v44, v[74:77] offset:52224
	s_waitcnt vmcnt(8)
	ds_write_b128 v44, v[66:69] offset:52352
	s_waitcnt lgkmcnt(0)
	s_barrier
; #define LDSBAR() do { asm volatile("s_waitcnt lgkmcnt(0)" ::: "memory"); __builtin_amdgcn_s_barrier(); asm volatile("" ::: "memory"); } while (0)
; #define SG_LOAD(R, s_) do { if ((s_) < ns) { R.a0 = NTL((const GAS v4u*)(ap + (s_) * 128)); R.a1 = NTL((const GAS v4u*)(ap + (s_) * 128 + 64)); R.b0 = NTL((const GAS v4u*)(bp + (s_) * 128)); R.b1 = NTL((const GAS v4u*)(bp + (s_) * 128 + 64)); } } while (0)
; #define SG_STORE(R, b_) do { *(LAS v4u*)(As + (b_) * BUF + prow * LDT + pk) = R.a0; *(LAS v4u*)(As + (b_) * BUF + prow * LDT + pk + 64) = R.a1; *(LAS v4u*)(Bs + (b_) * BUF + prow * LDT + pk) = R.b0; *(LAS v4u*)(Bs + (b_) * BUF + prow * LDT + pk + 64) = R.b1; } while (0)
; template <class Epi>
; __device__ __forceinline__ void small_gemm(const Frame& F, const bf16* A, const bf16* Bt, int row_base, int K, const Epi E) {
;     ...
;         SgPre R0, R1, R2, R3;
;         SG_LOAD(R0, 0); SG_LOAD(R1, 1); SG_LOAD(R2, 2);
;         SG_STORE(R0, 0); LDSBAR();
;         for (int s = 0; s < ns; s += 4) {
;             SG_LOAD(R3, s + 3); SG_COMP(0); if (s + 1 < ns) SG_STORE(R1, 1); LDSBAR(); if (s + 1 >= ns) break;
;             SG_LOAD(R0, s + 4); SG_COMP(1); if (s + 2 < ns) SG_STORE(R2, 0); LDSBAR(); if (s + 2 >= ns) break;
;             SG_LOAD(R1, s + 5); SG_COMP(0); if (s + 3 < ns) SG_STORE(R3, 1); LDSBAR(); if (s + 3 >= ns) break;
;             SG_LOAD(R2, s + 6); SG_COMP(1); if (s + 4 < ns) SG_STORE(R0, 0); LDSBAR();
	s_waitcnt lgkmcnt(5)
	v_mfma_f32_16x16x32_bf16 v[10:13], v[18:21], v[106:109], v[10:13]
	ds_read_b128 v[18:21], v43 offset:52224
	ds_read_b128 v[22:25], v42 offset:17408
	ds_read_b128 v[46:49], v42 offset:17472
	ds_read_b128 v[50:53], v43 offset:52288
	v_mfma_f32_16x16x32_bf16 v[14:17], v[82:85], v[102:105], v[14:17]
	s_waitcnt lgkmcnt(8)
	v_mfma_f32_16x16x32_bf16 v[14:17], v[78:81], v[106:109], v[14:17]
	s_waitcnt lgkmcnt(2)
	v_mfma_f32_16x16x32_bf16 v[10:13], v[18:21], v[22:25], v[10:13]
	ds_read_b128 v[18:21], v43 offset:56576
	ds_read_b128 v[66:69], v43 offset:56640
	s_waitcnt lgkmcnt(1)
	v_mfma_f32_16x16x32_bf16 v[14:17], v[18:21], v[22:25], v[14:17]
	ds_read_b128 v[18:21], v43 offset:52352
	v_mfma_f32_16x16x32_bf16 v[10:13], v[50:53], v[46:49], v[10:13]
	s_waitcnt lgkmcnt(1)
	v_mfma_f32_16x16x32_bf16 v[14:17], v[66:69], v[46:49], v[14:17]
	ds_read_b128 v[22:25], v42 offset:17536
	ds_read_b128 v[46:49], v42 offset:17600
	ds_read_b128 v[50:53], v43 offset:52416
	s_waitcnt lgkmcnt(2)
	v_mfma_f32_16x16x32_bf16 v[10:13], v[18:21], v[22:25], v[10:13]
	ds_read_b128 v[18:21], v43 offset:56704
	ds_read_b128 v[66:69], v43 offset:56768
	global_load_dwordx4 v[74:77], v[34:35], off offset:2048
	global_load_dwordx4 v[78:81], v[34:35], off offset:2176
	global_load_dwordx4 v[82:85], v[32:33], off offset:2048
	s_waitcnt lgkmcnt(2)
	v_mfma_f32_16x16x32_bf16 v[10:13], v[50:53], v[46:49], v[10:13]
	global_load_dwordx4 v[50:53], v[32:33], off offset:2176
	s_waitcnt vmcnt(11)
	ds_write_b128 v41, v[54:57]
	s_waitcnt vmcnt(10)
	ds_write_b128 v41, v[90:93] offset:128
	s_waitcnt vmcnt(9)
	ds_write_b128 v41, v[62:65] offset:34816
	s_waitcnt vmcnt(8)
	ds_write_b128 v41, v[70:73] offset:34944
	s_waitcnt lgkmcnt(0)
	s_waitcnt lgkmcnt(5)
	v_mfma_f32_16x16x32_bf16 v[14:17], v[18:21], v[22:25], v[14:17]
	s_barrier
	s_waitcnt lgkmcnt(4)
	v_mfma_f32_16x16x32_bf16 v[18:21], v[66:69], v[46:49], v[14:17]
	s_nop 4
	ds_read_b128 v[14:17], v43 offset:34816
	ds_read_b128 v[22:25], v43 offset:39168
	ds_read_b128 v[46:49], v42
	ds_read_b128 v[54:57], v42 offset:64
	ds_read_b128 v[62:65], v43 offset:34880
	s_waitcnt lgkmcnt(2)
	v_mfma_f32_16x16x32_bf16 v[66:69], v[14:17], v[46:49], v[10:13]
	s_nop 2
	global_load_dwordx4 v[10:13], v[34:35], off offset:2304
	global_load_dwordx4 v[14:17], v[34:35], off offset:2432
	ds_read_b128 v[70:73], v43 offset:39232
	v_mfma_f32_16x16x32_bf16 v[46:49], v[22:25], v[46:49], v[18:21]
	s_nop 2
	global_load_dwordx4 v[18:21], v[32:33], off offset:2304
	global_load_dwordx4 v[22:25], v[32:33], off offset:2432
	ds_read_b128 v[90:93], v43 offset:34944
	s_waitcnt lgkmcnt(2)
	v_mfma_f32_16x16x32_bf16 v[62:65], v[62:65], v[54:57], v[66:69]
	s_nop 2
	ds_read_b128 v[66:69], v43 offset:39296
	ds_read_b128 v[102:105], v42 offset:128
	ds_read_b128 v[106:109], v42 offset:192
	s_waitcnt lgkmcnt(4)
	v_mfma_f32_16x16x32_bf16 v[46:49], v[70:73], v[54:57], v[46:49]
	ds_read_b128 v[54:57], v43 offset:35008
	ds_read_b128 v[70:73], v43 offset:39360
	s_waitcnt vmcnt(11)
	ds_write_b128 v44, v[86:89] offset:17408
	s_waitcnt vmcnt(10)
	ds_write_b128 v44, v[94:97] offset:17536
	s_waitcnt vmcnt(9)
	ds_write_b128 v44, v[58:61] offset:52224
	s_waitcnt vmcnt(8)
	ds_write_b128 v44, v[98:101] offset:52352
	s_waitcnt lgkmcnt(7)
	v_mfma_f32_16x16x32_bf16 v[62:65], v[90:93], v[102:105], v[62:65]
	s_waitcnt lgkmcnt(0)
	s_barrier
	v_mfma_f32_16x16x32_bf16 v[46:49], v[66:69], v[102:105], v[46:49]
	s_waitcnt lgkmcnt(5)
	v_mfma_f32_16x16x32_bf16 v[54:57], v[54:57], v[106:109], v[62:65]
	ds_read_b128 v[58:61], v43 offset:52224
	s_nop 2
	ds_read_b128 v[62:65], v43 offset:56576
	s_waitcnt lgkmcnt(6)
	v_mfma_f32_16x16x32_bf16 v[46:49], v[70:73], v[106:109], v[46:49]
	ds_read_b128 v[66:69], v42 offset:17408
	ds_read_b128 v[70:73], v42 offset:17472
	ds_read_b128 v[86:89], v43 offset:52288
	s_waitcnt lgkmcnt(2)
	v_mfma_f32_16x16x32_bf16 v[54:57], v[58:61], v[66:69], v[54:57]
	global_load_dwordx4 v[58:61], v[34:35], off offset:2560
	global_load_dwordx4 v[90:93], v[34:35], off offset:2688
	ds_read_b128 v[94:97], v43 offset:56640
	v_mfma_f32_16x16x32_bf16 v[46:49], v[62:65], v[66:69], v[46:49]
	global_load_dwordx4 v[62:65], v[32:33], off offset:2560
	global_load_dwordx4 v[66:69], v[32:33], off offset:2688
	ds_read_b128 v[98:101], v43 offset:52352
	s_waitcnt lgkmcnt(2)
	v_mfma_f32_16x16x32_bf16 v[54:57], v[86:89], v[70:73], v[54:57]
	ds_read_b128 v[86:89], v43 offset:56704
	ds_read_b128 v[102:105], v42 offset:17536
	ds_read_b128 v[106:109], v42 offset:17600
	s_waitcnt lgkmcnt(4)
	v_mfma_f32_16x16x32_bf16 v[46:49], v[94:97], v[70:73], v[46:49]
	ds_read_b128 v[70:73], v43 offset:52416
	ds_read_b128 v[94:97], v43 offset:56768
	s_waitcnt vmcnt(11)
	ds_write_b128 v41, v[74:77]
	s_waitcnt lgkmcnt(4)
	v_mfma_f32_16x16x32_bf16 v[54:57], v[98:101], v[102:105], v[54:57]
	s_waitcnt vmcnt(10)
	ds_write_b128 v41, v[78:81] offset:128
	s_waitcnt vmcnt(9)
	ds_write_b128 v41, v[82:85] offset:34816
	s_waitcnt vmcnt(8)
	ds_write_b128 v41, v[50:53] offset:34944
	s_waitcnt lgkmcnt(0)
	s_barrier
; #define LDSBAR() do { asm volatile("s_waitcnt lgkmcnt(0)" ::: "memory"); __builtin_amdgcn_s_barrier(); asm volatile("" ::: "memory"); } while (0)
; #define SG_LOAD(R, s_) do { if ((s_) < ns) { R.a0 = NTL((const GAS v4u*)(ap + (s_) * 128)); R.a1 = NTL((const GAS v4u*)(ap + (s_) * 128 + 64)); R.b0 = NTL((const GAS v4u*)(bp + (s_) * 128)); R.b1 = NTL((const GAS v4u*)(bp + (s_) * 128 + 64)); } } while (0)
; #define SG_STORE(R, b_) do { *(LAS v4u*)(As + (b_) * BUF + prow * LDT + pk) = R.a0; *(LAS v4u*)(As + (b_) * BUF + prow * LDT + pk + 64) = R.a1; *(LAS v4u*)(Bs + (b_) * BUF + prow * LDT + pk) = R.b0; *(LAS v4u*)(Bs + (b_) * BUF + prow * LDT + pk + 64) = R.b1; } while (0)
; template <class Epi>
; __device__ __forceinline__ void small_gemm(const Frame& F, const bf16* A, const bf16* Bt, int row_base, int K, const Epi E) {
;     ...
;         SgPre R0, R1, R2, R3;
;         SG_LOAD(R0, 0); SG_LOAD(R1, 1); SG_LOAD(R2, 2);
;         SG_STORE(R0, 0); LDSBAR();
;         for (int s = 0; s < ns; s += 4) {
;             SG_LOAD(R3, s + 3); SG_COMP(0); if (s + 1 < ns) SG_STORE(R1, 1); LDSBAR(); if (s + 1 >= ns) break;
;             SG_LOAD(R0, s + 4); SG_COMP(1); if (s + 2 < ns) SG_STORE(R2, 0); LDSBAR(); if (s + 2 >= ns) break;
;             SG_LOAD(R1, s + 5); SG_COMP(0); if (s + 3 < ns) SG_STORE(R3, 1); LDSBAR(); if (s + 3 >= ns) break;
;             SG_LOAD(R2, s + 6); SG_COMP(1); if (s + 4 < ns) SG_STORE(R0, 0); LDSBAR();
	s_waitcnt lgkmcnt(5)
	v_mfma_f32_16x16x32_bf16 v[50:53], v[70:73], v[106:109], v[54:57]
	s_nop 2
	ds_read_b128 v[54:57], v43 offset:34816
	v_mfma_f32_16x16x32_bf16 v[46:49], v[86:89], v[102:105], v[46:49]
	ds_read_b128 v[70:73], v42
	ds_read_b128 v[74:77], v42 offset:64
	ds_read_b128 v[78:81], v43 offset:34880
	s_waitcnt lgkmcnt(8)
	v_mfma_f32_16x16x32_bf16 v[46:49], v[94:97], v[106:109], v[46:49]
	s_waitcnt lgkmcnt(2)
	v_mfma_f32_16x16x32_bf16 v[50:53], v[54:57], v[70:73], v[50:53]
	ds_read_b128 v[54:57], v43 offset:39168
	ds_read_b128 v[82:85], v43 offset:39232
	s_waitcnt lgkmcnt(1)
	v_mfma_f32_16x16x32_bf16 v[46:49], v[54:57], v[70:73], v[46:49]
	ds_read_b128 v[54:57], v43 offset:34944
	v_mfma_f32_16x16x32_bf16 v[50:53], v[78:81], v[74:77], v[50:53]
	s_waitcnt lgkmcnt(1)
	v_mfma_f32_16x16x32_bf16 v[46:49], v[82:85], v[74:77], v[46:49]
	ds_read_b128 v[70:73], v42 offset:128
	ds_read_b128 v[74:77], v42 offset:192
	ds_read_b128 v[78:81], v43 offset:35008
	s_waitcnt lgkmcnt(2)
	v_mfma_f32_16x16x32_bf16 v[50:53], v[54:57], v[70:73], v[50:53]
	ds_read_b128 v[54:57], v43 offset:39296
	ds_read_b128 v[82:85], v43 offset:39360
	s_waitcnt lgkmcnt(1)
	v_mfma_f32_16x16x32_bf16 v[46:49], v[54:57], v[70:73], v[46:49]
	global_load_dwordx4 v[54:57], v[34:35], off offset:2816
	global_load_dwordx4 v[70:73], v[34:35], off offset:2944
	global_load_dwordx4 v[86:89], v[32:33], off offset:2816
	v_mfma_f32_16x16x32_bf16 v[50:53], v[78:81], v[74:77], v[50:53]
	global_load_dwordx4 v[78:81], v[32:33], off offset:2944
	s_waitcnt vmcnt(11)
	ds_write_b128 v44, v[10:13] offset:17408
	s_waitcnt vmcnt(10)
	ds_write_b128 v44, v[14:17] offset:17536
	s_waitcnt vmcnt(9)
	ds_write_b128 v44, v[18:21] offset:52224
	s_waitcnt vmcnt(8)
	ds_write_b128 v44, v[22:25] offset:52352
	s_waitcnt lgkmcnt(0)
	s_barrier
	s_waitcnt lgkmcnt(4)
	v_mfma_f32_16x16x32_bf16 v[46:49], v[82:85], v[74:77], v[46:49]
	ds_read_b128 v[10:13], v43 offset:52224
	ds_read_b128 v[14:17], v43 offset:56576
	ds_read_b128 v[18:21], v42 offset:17408
	ds_read_b128 v[22:25], v42 offset:17472
	ds_read_b128 v[74:77], v43 offset:52288
	s_waitcnt lgkmcnt(2)
	v_mfma_f32_16x16x32_bf16 v[10:13], v[10:13], v[18:21], v[50:53]
	s_nop 2
	global_load_dwordx4 v[50:53], v[34:35], off offset:3072
	global_load_dwordx4 v[82:85], v[34:35], off offset:3200
	ds_read_b128 v[94:97], v43 offset:56640
	v_mfma_f32_16x16x32_bf16 v[14:17], v[14:17], v[18:21], v[46:49]
	global_load_dwordx4 v[18:21], v[32:33], off offset:3072
	s_nop 1
	global_load_dwordx4 v[46:49], v[32:33], off offset:3200
	ds_read_b128 v[98:101], v43 offset:52352
	s_waitcnt lgkmcnt(2)
	v_mfma_f32_16x16x32_bf16 v[10:13], v[74:77], v[22:25], v[10:13]
	ds_read_b128 v[74:77], v43 offset:56704
	ds_read_b128 v[102:105], v42 offset:17536
	ds_read_b128 v[106:109], v42 offset:17600
	s_waitcnt lgkmcnt(4)
	v_mfma_f32_16x16x32_bf16 v[14:17], v[94:97], v[22:25], v[14:17]
	ds_read_b128 v[22:25], v43 offset:52416
	ds_read_b128 v[94:97], v43 offset:56768
	s_waitcnt vmcnt(11)
	ds_write_b128 v41, v[58:61]
	s_waitcnt vmcnt(10)
	ds_write_b128 v41, v[90:93] offset:128
	s_waitcnt vmcnt(9)
	ds_write_b128 v41, v[62:65] offset:34816
	s_waitcnt vmcnt(8)
	ds_write_b128 v41, v[66:69] offset:34944
	s_waitcnt lgkmcnt(7)
	v_mfma_f32_16x16x32_bf16 v[10:13], v[98:101], v[102:105], v[10:13]
	s_waitcnt lgkmcnt(0)
	s_barrier
	v_mfma_f32_16x16x32_bf16 v[14:17], v[74:77], v[102:105], v[14:17]
	s_waitcnt lgkmcnt(5)
	v_mfma_f32_16x16x32_bf16 v[10:13], v[22:25], v[106:109], v[10:13]
	ds_read_b128 v[22:25], v43 offset:34816
	ds_read_b128 v[58:61], v43 offset:39168
	ds_read_b128 v[62:65], v42
	ds_read_b128 v[66:69], v42 offset:64
	ds_read_b128 v[74:77], v43 offset:34880
	s_waitcnt lgkmcnt(9)
	v_mfma_f32_16x16x32_bf16 v[14:17], v[94:97], v[106:109], v[14:17]
	s_waitcnt lgkmcnt(2)
	v_mfma_f32_16x16x32_bf16 v[10:13], v[22:25], v[62:65], v[10:13]
	global_load_dwordx4 v[22:25], v[34:35], off offset:3328
	global_load_dwordx4 v[90:93], v[34:35], off offset:3456
	ds_read_b128 v[94:97], v43 offset:39232
	v_mfma_f32_16x16x32_bf16 v[14:17], v[58:61], v[62:65], v[14:17]
	global_load_dwordx4 v[58:61], v[32:33], off offset:3328
	global_load_dwordx4 v[62:65], v[32:33], off offset:3456
	ds_read_b128 v[98:101], v43 offset:34944
	s_waitcnt lgkmcnt(2)
	v_mfma_f32_16x16x32_bf16 v[10:13], v[74:77], v[66:69], v[10:13]
	ds_read_b128 v[74:77], v43 offset:39296
	ds_read_b128 v[102:105], v42 offset:128
	ds_read_b128 v[106:109], v42 offset:192
	s_waitcnt lgkmcnt(4)
	v_mfma_f32_16x16x32_bf16 v[14:17], v[94:97], v[66:69], v[14:17]
	ds_read_b128 v[66:69], v43 offset:35008
	ds_read_b128 v[94:97], v43 offset:39360
	s_waitcnt vmcnt(11)
	ds_write_b128 v44, v[54:57] offset:17408
	s_waitcnt vmcnt(10)
	ds_write_b128 v44, v[70:73] offset:17536
	s_waitcnt vmcnt(9)
	ds_write_b128 v44, v[86:89] offset:52224
	s_waitcnt vmcnt(8)
	ds_write_b128 v44, v[78:81] offset:52352
	s_waitcnt lgkmcnt(0)
	s_barrier
; #define LDSBAR() do { asm volatile("s_waitcnt lgkmcnt(0)" ::: "memory"); __builtin_amdgcn_s_barrier(); asm volatile("" ::: "memory"); } while (0)
; #define SG_LOAD(R, s_) do { if ((s_) < ns) { R.a0 = NTL((const GAS v4u*)(ap + (s_) * 128)); R.a1 = NTL((const GAS v4u*)(ap + (s_) * 128 + 64)); R.b0 = NTL((const GAS v4u*)(bp + (s_) * 128)); R.b1 = NTL((const GAS v4u*)(bp + (s_) * 128 + 64)); } } while (0)
; #define SG_STORE(R, b_) do { *(LAS v4u*)(As + (b_) * BUF + prow * LDT + pk) = R.a0; *(LAS v4u*)(As + (b_) * BUF + prow * LDT + pk + 64) = R.a1; *(LAS v4u*)(Bs + (b_) * BUF + prow * LDT + pk) = R.b0; *(LAS v4u*)(Bs + (b_) * BUF + prow * LDT + pk + 64) = R.b1; } while (0)
; template <class Epi>
; __device__ __forceinline__ void small_gemm(const Frame& F, const bf16* A, const bf16* Bt, int row_base, int K, const Epi E) {
;     ...
;         SgPre R0, R1, R2, R3;
;         SG_LOAD(R0, 0); SG_LOAD(R1, 1); SG_LOAD(R2, 2);
;         SG_STORE(R0, 0); LDSBAR();
;         for (int s = 0; s < ns; s += 4) {
;             SG_LOAD(R3, s + 3); SG_COMP(0); if (s + 1 < ns) SG_STORE(R1, 1); LDSBAR(); if (s + 1 >= ns) break;
;             SG_LOAD(R0, s + 4); SG_COMP(1); if (s + 2 < ns) SG_STORE(R2, 0); LDSBAR(); if (s + 2 >= ns) break;
;             SG_LOAD(R1, s + 5); SG_COMP(0); if (s + 3 < ns) SG_STORE(R3, 1); LDSBAR(); if (s + 3 >= ns) break;
;             SG_LOAD(R2, s + 6); SG_COMP(1); if (s + 4 < ns) SG_STORE(R0, 0); LDSBAR();
	ds_read_b128 v[54:57], v43 offset:52224
	s_waitcnt lgkmcnt(8)
	v_mfma_f32_16x16x32_bf16 v[10:13], v[98:101], v[102:105], v[10:13]
	v_mfma_f32_16x16x32_bf16 v[14:17], v[74:77], v[102:105], v[14:17]
	s_waitcnt lgkmcnt(6)
	v_mfma_f32_16x16x32_bf16 v[10:13], v[66:69], v[106:109], v[10:13]
	ds_read_b128 v[66:69], v42 offset:17408
	ds_read_b128 v[70:73], v42 offset:17472
	ds_read_b128 v[74:77], v43 offset:52288
	s_waitcnt lgkmcnt(8)
	v_mfma_f32_16x16x32_bf16 v[14:17], v[94:97], v[106:109], v[14:17]
	s_waitcnt lgkmcnt(2)
	v_mfma_f32_16x16x32_bf16 v[54:57], v[54:57], v[66:69], v[10:13]
	s_nop 2
	ds_read_b128 v[10:13], v43 offset:56576
	ds_read_b128 v[78:81], v43 offset:56640
	s_waitcnt lgkmcnt(1)
	v_mfma_f32_16x16x32_bf16 v[12:15], v[10:13], v[66:69], v[14:17]
	ds_read_b128 v[66:69], v43 offset:52352
	v_add_co_u32_e32 v10, vcc, s13, v34
	v_mfma_f32_16x16x32_bf16 v[54:57], v[74:77], v[70:73], v[54:57]
	s_nop 0
	v_addc_co_u32_e32 v11, vcc, 0, v35, vcc
	s_waitcnt lgkmcnt(1)
	v_mfma_f32_16x16x32_bf16 v[12:15], v[78:81], v[70:73], v[12:15]
	ds_read_b128 v[70:73], v42 offset:17536
	ds_read_b128 v[74:77], v42 offset:17600
	ds_read_b128 v[78:81], v43 offset:52416
	s_waitcnt lgkmcnt(2)
	v_mfma_f32_16x16x32_bf16 v[54:57], v[66:69], v[70:73], v[54:57]
	ds_read_b128 v[66:69], v43 offset:56704
	ds_read_b128 v[86:89], v43 offset:56768
	s_waitcnt lgkmcnt(1)
	v_mfma_f32_16x16x32_bf16 v[12:15], v[66:69], v[70:73], v[12:15]
	global_load_dwordx4 v[66:69], v[34:35], off offset:3584
	global_load_dwordx4 v[70:73], v[34:35], off offset:3712
	global_load_dwordx4 v[94:97], v[32:33], off offset:3584
	v_mfma_f32_16x16x32_bf16 v[54:57], v[78:81], v[74:77], v[54:57]
	global_load_dwordx4 v[78:81], v[32:33], off offset:3712
	s_waitcnt vmcnt(11)
	ds_write_b128 v41, v[50:53]
	s_waitcnt vmcnt(10)
	ds_write_b128 v41, v[82:85] offset:128
	s_waitcnt vmcnt(9)
	ds_write_b128 v41, v[18:21] offset:34816
	s_waitcnt vmcnt(8)
	ds_write_b128 v41, v[46:49] offset:34944
	s_waitcnt lgkmcnt(0)
	s_barrier
	s_waitcnt lgkmcnt(4)
	v_mfma_f32_16x16x32_bf16 v[12:15], v[86:89], v[74:77], v[12:15]
	ds_read_b128 v[16:19], v43 offset:34816
	ds_read_b128 v[46:49], v43 offset:39168
	ds_read_b128 v[50:53], v42
	ds_read_b128 v[74:77], v42 offset:64
	ds_read_b128 v[82:85], v43 offset:34880
	s_waitcnt lgkmcnt(2)
	v_mfma_f32_16x16x32_bf16 v[16:19], v[16:19], v[50:53], v[54:57]
	s_nop 2
	global_load_dwordx4 v[54:57], v[34:35], off offset:3840
	global_load_dwordx4 v[86:89], v[34:35], off offset:3968
	ds_read_b128 v[98:101], v43 offset:39232
	v_mfma_f32_16x16x32_bf16 v[12:15], v[46:49], v[50:53], v[12:15]
	global_load_dwordx4 v[46:49], v[32:33], off offset:3840
	global_load_dwordx4 v[50:53], v[32:33], off offset:3968
	ds_read_b128 v[32:35], v43 offset:34944
	s_waitcnt lgkmcnt(2)
	v_mfma_f32_16x16x32_bf16 v[16:19], v[82:85], v[74:77], v[16:19]
	ds_read_b128 v[82:85], v43 offset:39296
	ds_read_b128 v[102:105], v42 offset:128
	ds_read_b128 v[106:109], v42 offset:192
	s_waitcnt lgkmcnt(4)
	v_mfma_f32_16x16x32_bf16 v[12:15], v[98:101], v[74:77], v[12:15]
	ds_read_b128 v[74:77], v43 offset:35008
	ds_read_b128 v[98:101], v43 offset:39360
	s_waitcnt vmcnt(11)
	ds_write_b128 v44, v[22:25] offset:17408
	s_waitcnt vmcnt(10)
	ds_write_b128 v44, v[90:93] offset:17536
	s_waitcnt vmcnt(9)
	ds_write_b128 v44, v[58:61] offset:52224
	s_waitcnt vmcnt(8)
	ds_write_b128 v44, v[62:65] offset:52352
	s_waitcnt lgkmcnt(7)
	v_mfma_f32_16x16x32_bf16 v[16:19], v[32:35], v[102:105], v[16:19]
	s_waitcnt lgkmcnt(0)
	s_barrier
	v_mfma_f32_16x16x32_bf16 v[12:15], v[82:85], v[102:105], v[12:15]
	ds_read_b128 v[20:23], v43 offset:52224
	ds_read_b128 v[32:35], v43 offset:56576
	s_waitcnt lgkmcnt(7)
	v_mfma_f32_16x16x32_bf16 v[16:19], v[74:77], v[106:109], v[16:19]
	ds_read_b128 v[58:61], v42 offset:17408
	ds_read_b128 v[62:65], v42 offset:17472
	ds_read_b128 v[74:77], v43 offset:52288
	s_waitcnt lgkmcnt(9)
	v_mfma_f32_16x16x32_bf16 v[12:15], v[98:101], v[106:109], v[12:15]
	s_waitcnt lgkmcnt(2)
	v_mfma_f32_16x16x32_bf16 v[16:19], v[20:23], v[58:61], v[16:19]
	global_load_dwordx4 v[20:23], v[10:11], off
	global_load_dwordx4 v[82:85], v[10:11], off offset:128
	ds_read_b128 v[90:93], v43 offset:56640
	v_mfma_f32_16x16x32_bf16 v[12:15], v[32:35], v[58:61], v[12:15]
	global_load_dwordx4 v[32:35], v[36:37], off
	global_load_dwordx4 v[58:61], v[36:37], off offset:128
	ds_read_b128 v[98:101], v43 offset:52352
	s_waitcnt lgkmcnt(2)
	v_mfma_f32_16x16x32_bf16 v[16:19], v[74:77], v[62:65], v[16:19]
	ds_read_b128 v[74:77], v43 offset:56704
	ds_read_b128 v[102:105], v42 offset:17536
	ds_read_b128 v[106:109], v42 offset:17600
	s_waitcnt lgkmcnt(4)
	v_mfma_f32_16x16x32_bf16 v[12:15], v[90:93], v[62:65], v[12:15]
	ds_read_b128 v[62:65], v43 offset:52416
	ds_read_b128 v[90:93], v43 offset:56768
	s_waitcnt vmcnt(11)
	ds_write_b128 v41, v[66:69]
	s_waitcnt lgkmcnt(4)
	v_mfma_f32_16x16x32_bf16 v[16:19], v[98:101], v[102:105], v[16:19]
	s_waitcnt vmcnt(10)
	ds_write_b128 v41, v[70:73] offset:128
	s_waitcnt vmcnt(9)
	ds_write_b128 v41, v[94:97] offset:34816
	s_waitcnt vmcnt(8)
	ds_write_b128 v41, v[78:81] offset:34944
	s_waitcnt lgkmcnt(0)
	s_barrier
; #define LDSBAR() do { asm volatile("s_waitcnt lgkmcnt(0)" ::: "memory"); __builtin_amdgcn_s_barrier(); asm volatile("" ::: "memory"); } while (0)
; #define SG_LOAD(R, s_) do { if ((s_) < ns) { R.a0 = NTL((const GAS v4u*)(ap + (s_) * 128)); R.a1 = NTL((const GAS v4u*)(ap + (s_) * 128 + 64)); R.b0 = NTL((const GAS v4u*)(bp + (s_) * 128)); R.b1 = NTL((const GAS v4u*)(bp + (s_) * 128 + 64)); } } while (0)
; #define SG_STORE(R, b_) do { *(LAS v4u*)(As + (b_) * BUF + prow * LDT + pk) = R.a0; *(LAS v4u*)(As + (b_) * BUF + prow * LDT + pk + 64) = R.a1; *(LAS v4u*)(Bs + (b_) * BUF + prow * LDT + pk) = R.b0; *(LAS v4u*)(Bs + (b_) * BUF + prow * LDT + pk + 64) = R.b1; } while (0)
; template <class Epi>
; __device__ __forceinline__ void small_gemm(const Frame& F, const bf16* A, const bf16* Bt, int row_base, int K, const Epi E) {
;     ...
;         SgPre R0, R1, R2, R3;
;         SG_LOAD(R0, 0); SG_LOAD(R1, 1); SG_LOAD(R2, 2);
;         SG_STORE(R0, 0); LDSBAR();
;         for (int s = 0; s < ns; s += 4) {
;             SG_LOAD(R3, s + 3); SG_COMP(0); if (s + 1 < ns) SG_STORE(R1, 1); LDSBAR(); if (s + 1 >= ns) break;
;             SG_LOAD(R0, s + 4); SG_COMP(1); if (s + 2 < ns) SG_STORE(R2, 0); LDSBAR(); if (s + 2 >= ns) break;
;             SG_LOAD(R1, s + 5); SG_COMP(0); if (s + 3 < ns) SG_STORE(R3, 1); LDSBAR(); if (s + 3 >= ns) break;
;             SG_LOAD(R2, s + 6); SG_COMP(1); if (s + 4 < ns) SG_STORE(R0, 0); LDSBAR();
	s_waitcnt lgkmcnt(5)
	v_mfma_f32_16x16x32_bf16 v[16:19], v[62:65], v[106:109], v[16:19]
	ds_read_b128 v[62:65], v43 offset:34816
	v_mfma_f32_16x16x32_bf16 v[12:15], v[74:77], v[102:105], v[12:15]
	ds_read_b128 v[66:69], v42
	ds_read_b128 v[70:73], v42 offset:64
	ds_read_b128 v[74:77], v43 offset:34880
	s_waitcnt lgkmcnt(8)
	v_mfma_f32_16x16x32_bf16 v[12:15], v[90:93], v[106:109], v[12:15]
	s_waitcnt lgkmcnt(2)
	v_mfma_f32_16x16x32_bf16 v[16:19], v[62:65], v[66:69], v[16:19]
	ds_read_b128 v[62:65], v43 offset:39168
	ds_read_b128 v[78:81], v43 offset:39232
	s_waitcnt lgkmcnt(1)
	v_mfma_f32_16x16x32_bf16 v[12:15], v[62:65], v[66:69], v[12:15]
	ds_read_b128 v[62:65], v43 offset:34944
	v_mfma_f32_16x16x32_bf16 v[16:19], v[74:77], v[70:73], v[16:19]
	s_waitcnt lgkmcnt(1)
	v_mfma_f32_16x16x32_bf16 v[12:15], v[78:81], v[70:73], v[12:15]
	ds_read_b128 v[66:69], v42 offset:128
	ds_read_b128 v[70:73], v42 offset:192
	ds_read_b128 v[74:77], v43 offset:35008
	s_waitcnt lgkmcnt(2)
	v_mfma_f32_16x16x32_bf16 v[16:19], v[62:65], v[66:69], v[16:19]
	ds_read_b128 v[62:65], v43 offset:39296
	ds_read_b128 v[78:81], v43 offset:39360
	s_waitcnt lgkmcnt(1)
	v_mfma_f32_16x16x32_bf16 v[12:15], v[62:65], v[66:69], v[12:15]
	global_load_dwordx4 v[62:65], v[10:11], off offset:256
	global_load_dwordx4 v[66:69], v[10:11], off offset:384
	global_load_dwordx4 v[90:93], v[36:37], off offset:256
	v_mfma_f32_16x16x32_bf16 v[16:19], v[74:77], v[70:73], v[16:19]
	global_load_dwordx4 v[74:77], v[36:37], off offset:384
	s_waitcnt vmcnt(11)
	ds_write_b128 v44, v[54:57] offset:17408
	s_waitcnt vmcnt(10)
	ds_write_b128 v44, v[86:89] offset:17536
	s_waitcnt vmcnt(9)
	ds_write_b128 v44, v[46:49] offset:52224
	s_waitcnt vmcnt(8)
	ds_write_b128 v44, v[50:53] offset:52352
	s_waitcnt lgkmcnt(0)
	s_waitcnt lgkmcnt(4)
	v_mfma_f32_16x16x32_bf16 v[12:15], v[78:81], v[70:73], v[12:15]
	s_barrier
	ds_read_b128 v[46:49], v43 offset:52224
	ds_read_b128 v[50:53], v43 offset:56576
	ds_read_b128 v[54:57], v42 offset:17408
	ds_read_b128 v[70:73], v42 offset:17472
	ds_read_b128 v[78:81], v43 offset:52288
	s_waitcnt lgkmcnt(2)
	v_mfma_f32_16x16x32_bf16 v[16:19], v[46:49], v[54:57], v[16:19]
	global_load_dwordx4 v[46:49], v[10:11], off offset:512
	global_load_dwordx4 v[86:89], v[10:11], off offset:640
	ds_read_b128 v[94:97], v43 offset:56640
	v_mfma_f32_16x16x32_bf16 v[12:15], v[50:53], v[54:57], v[12:15]
	global_load_dwordx4 v[50:53], v[36:37], off offset:512
	global_load_dwordx4 v[54:57], v[36:37], off offset:640
	ds_read_b128 v[98:101], v43 offset:52352
	s_waitcnt lgkmcnt(2)
	v_mfma_f32_16x16x32_bf16 v[16:19], v[78:81], v[70:73], v[16:19]
	ds_read_b128 v[78:81], v43 offset:56704
	ds_read_b128 v[102:105], v42 offset:17536
	ds_read_b128 v[106:109], v42 offset:17600
	s_waitcnt lgkmcnt(4)
	v_mfma_f32_16x16x32_bf16 v[12:15], v[94:97], v[70:73], v[12:15]
	ds_read_b128 v[70:73], v43 offset:52416
	ds_read_b128 v[94:97], v43 offset:56768
	s_waitcnt vmcnt(11)
	ds_write_b128 v41, v[20:23]
	s_waitcnt vmcnt(10)
	ds_write_b128 v41, v[82:85] offset:128
	s_waitcnt vmcnt(9)
	ds_write_b128 v41, v[32:35] offset:34816
	s_waitcnt vmcnt(8)
	ds_write_b128 v41, v[58:61] offset:34944
	s_waitcnt lgkmcnt(7)
	v_mfma_f32_16x16x32_bf16 v[16:19], v[98:101], v[102:105], v[16:19]
	s_waitcnt lgkmcnt(0)
	s_barrier
	v_mfma_f32_16x16x32_bf16 v[12:15], v[78:81], v[102:105], v[12:15]
	ds_read_b128 v[20:23], v43 offset:34816
	ds_read_b128 v[32:35], v43 offset:39168
	s_waitcnt lgkmcnt(7)
	v_mfma_f32_16x16x32_bf16 v[16:19], v[70:73], v[106:109], v[16:19]
	ds_read_b128 v[58:61], v42
	ds_read_b128 v[70:73], v42 offset:64
	ds_read_b128 v[78:81], v43 offset:34880
	s_waitcnt lgkmcnt(9)
	v_mfma_f32_16x16x32_bf16 v[12:15], v[94:97], v[106:109], v[12:15]
	s_waitcnt lgkmcnt(2)
	v_mfma_f32_16x16x32_bf16 v[16:19], v[20:23], v[58:61], v[16:19]
	global_load_dwordx4 v[20:23], v[10:11], off offset:768
	global_load_dwordx4 v[82:85], v[10:11], off offset:896
	ds_read_b128 v[94:97], v43 offset:39232
	v_mfma_f32_16x16x32_bf16 v[12:15], v[32:35], v[58:61], v[12:15]
	global_load_dwordx4 v[32:35], v[36:37], off offset:768
	global_load_dwordx4 v[58:61], v[36:37], off offset:896
	ds_read_b128 v[98:101], v43 offset:34944
	s_waitcnt lgkmcnt(2)
	v_mfma_f32_16x16x32_bf16 v[16:19], v[78:81], v[70:73], v[16:19]
	ds_read_b128 v[78:81], v43 offset:39296
	ds_read_b128 v[102:105], v42 offset:128
	ds_read_b128 v[106:109], v42 offset:192
	s_waitcnt lgkmcnt(4)
	v_mfma_f32_16x16x32_bf16 v[12:15], v[94:97], v[70:73], v[12:15]
	ds_read_b128 v[70:73], v43 offset:35008
	ds_read_b128 v[94:97], v43 offset:39360
	s_waitcnt vmcnt(11)
	ds_write_b128 v44, v[62:65] offset:17408
	s_waitcnt vmcnt(10)
	ds_write_b128 v44, v[66:69] offset:17536
	s_waitcnt vmcnt(9)
	ds_write_b128 v44, v[90:93] offset:52224
	s_waitcnt vmcnt(8)
	ds_write_b128 v44, v[74:77] offset:52352
	s_waitcnt lgkmcnt(0)
	s_barrier
; #define LDSBAR() do { asm volatile("s_waitcnt lgkmcnt(0)" ::: "memory"); __builtin_amdgcn_s_barrier(); asm volatile("" ::: "memory"); } while (0)
; #define SG_LOAD(R, s_) do { if ((s_) < ns) { R.a0 = NTL((const GAS v4u*)(ap + (s_) * 128)); R.a1 = NTL((const GAS v4u*)(ap + (s_) * 128 + 64)); R.b0 = NTL((const GAS v4u*)(bp + (s_) * 128)); R.b1 = NTL((const GAS v4u*)(bp + (s_) * 128 + 64)); } } while (0)
; #define SG_STORE(R, b_) do { *(LAS v4u*)(As + (b_) * BUF + prow * LDT + pk) = R.a0; *(LAS v4u*)(As + (b_) * BUF + prow * LDT + pk + 64) = R.a1; *(LAS v4u*)(Bs + (b_) * BUF + prow * LDT + pk) = R.b0; *(LAS v4u*)(Bs + (b_) * BUF + prow * LDT + pk + 64) = R.b1; } while (0)
; template <class Epi>
; __device__ __forceinline__ void small_gemm(const Frame& F, const bf16* A, const bf16* Bt, int row_base, int K, const Epi E) {
;     ...
;         SgPre R0, R1, R2, R3;
;         SG_LOAD(R0, 0); SG_LOAD(R1, 1); SG_LOAD(R2, 2);
;         SG_STORE(R0, 0); LDSBAR();
;         for (int s = 0; s < ns; s += 4) {
;             SG_LOAD(R3, s + 3); SG_COMP(0); if (s + 1 < ns) SG_STORE(R1, 1); LDSBAR(); if (s + 1 >= ns) break;
;             SG_LOAD(R0, s + 4); SG_COMP(1); if (s + 2 < ns) SG_STORE(R2, 0); LDSBAR(); if (s + 2 >= ns) break;
;             SG_LOAD(R1, s + 5); SG_COMP(0); if (s + 3 < ns) SG_STORE(R3, 1); LDSBAR(); if (s + 3 >= ns) break;
;             SG_LOAD(R2, s + 6); SG_COMP(1); if (s + 4 < ns) SG_STORE(R0, 0); LDSBAR();
	ds_read_b128 v[62:65], v43 offset:52224
	s_waitcnt lgkmcnt(8)
	v_mfma_f32_16x16x32_bf16 v[16:19], v[98:101], v[102:105], v[16:19]
	v_mfma_f32_16x16x32_bf16 v[12:15], v[78:81], v[102:105], v[12:15]
	s_waitcnt lgkmcnt(6)
	v_mfma_f32_16x16x32_bf16 v[16:19], v[70:73], v[106:109], v[16:19]
	ds_read_b128 v[66:69], v42 offset:17408
	ds_read_b128 v[70:73], v42 offset:17472
	ds_read_b128 v[74:77], v43 offset:52288
	s_waitcnt lgkmcnt(8)
	v_mfma_f32_16x16x32_bf16 v[12:15], v[94:97], v[106:109], v[12:15]
	s_waitcnt lgkmcnt(2)
	v_mfma_f32_16x16x32_bf16 v[16:19], v[62:65], v[66:69], v[16:19]
	ds_read_b128 v[62:65], v43 offset:56576
	ds_read_b128 v[78:81], v43 offset:56640
	s_waitcnt lgkmcnt(1)
	v_mfma_f32_16x16x32_bf16 v[12:15], v[62:65], v[66:69], v[12:15]
	ds_read_b128 v[62:65], v43 offset:52352
	v_mfma_f32_16x16x32_bf16 v[16:19], v[74:77], v[70:73], v[16:19]
	s_waitcnt lgkmcnt(1)
	v_mfma_f32_16x16x32_bf16 v[12:15], v[78:81], v[70:73], v[12:15]
	ds_read_b128 v[66:69], v42 offset:17536
	ds_read_b128 v[70:73], v42 offset:17600
	ds_read_b128 v[74:77], v43 offset:52416
	s_waitcnt lgkmcnt(2)
	v_mfma_f32_16x16x32_bf16 v[16:19], v[62:65], v[66:69], v[16:19]
	ds_read_b128 v[62:65], v43 offset:56704
	ds_read_b128 v[78:81], v43 offset:56768
	s_waitcnt lgkmcnt(1)
	v_mfma_f32_16x16x32_bf16 v[12:15], v[62:65], v[66:69], v[12:15]
	global_load_dwordx4 v[62:65], v[10:11], off offset:1024
	global_load_dwordx4 v[66:69], v[10:11], off offset:1152
	global_load_dwordx4 v[90:93], v[36:37], off offset:1024
	v_mfma_f32_16x16x32_bf16 v[16:19], v[74:77], v[70:73], v[16:19]
	global_load_dwordx4 v[74:77], v[36:37], off offset:1152
	s_waitcnt vmcnt(11)
	ds_write_b128 v41, v[46:49]
	s_waitcnt vmcnt(10)
	ds_write_b128 v41, v[86:89] offset:128
	s_waitcnt vmcnt(9)
	ds_write_b128 v41, v[50:53] offset:34816
	s_waitcnt vmcnt(8)
	ds_write_b128 v41, v[54:57] offset:34944
	s_waitcnt lgkmcnt(0)
	s_waitcnt lgkmcnt(4)
	v_mfma_f32_16x16x32_bf16 v[12:15], v[78:81], v[70:73], v[12:15]
	s_barrier
	ds_read_b128 v[46:49], v43 offset:34816
	ds_read_b128 v[50:53], v43 offset:39168
	ds_read_b128 v[54:57], v42
	ds_read_b128 v[70:73], v42 offset:64
	ds_read_b128 v[78:81], v43 offset:34880
	s_waitcnt lgkmcnt(2)
	v_mfma_f32_16x16x32_bf16 v[16:19], v[46:49], v[54:57], v[16:19]
	global_load_dwordx4 v[46:49], v[10:11], off offset:1280
	global_load_dwordx4 v[86:89], v[10:11], off offset:1408
	ds_read_b128 v[94:97], v43 offset:39232
	v_mfma_f32_16x16x32_bf16 v[10:13], v[50:53], v[54:57], v[12:15]
	global_load_dwordx4 v[50:53], v[36:37], off offset:1280
	global_load_dwordx4 v[54:57], v[36:37], off offset:1408
	ds_read_b128 v[98:101], v43 offset:34944
	s_waitcnt lgkmcnt(2)
	v_mfma_f32_16x16x32_bf16 v[14:17], v[78:81], v[70:73], v[16:19]
	ds_read_b128 v[78:81], v43 offset:39296
	ds_read_b128 v[102:105], v42 offset:128
	ds_read_b128 v[106:109], v42 offset:192
	s_waitcnt lgkmcnt(4)
	v_mfma_f32_16x16x32_bf16 v[10:13], v[94:97], v[70:73], v[10:13]
	ds_read_b128 v[70:73], v43 offset:35008
	ds_read_b128 v[94:97], v43 offset:39360
	s_waitcnt vmcnt(11)
	ds_write_b128 v44, v[20:23] offset:17408
	s_waitcnt vmcnt(10)
	ds_write_b128 v44, v[82:85] offset:17536
	s_waitcnt vmcnt(9)
	ds_write_b128 v44, v[32:35] offset:52224
	s_waitcnt vmcnt(8)
	ds_write_b128 v44, v[58:61] offset:52352
	s_waitcnt lgkmcnt(0)
	s_barrier
; #define LDSBAR() do { asm volatile("s_waitcnt lgkmcnt(0)" ::: "memory"); __builtin_amdgcn_s_barrier(); asm volatile("" ::: "memory"); } while (0)
; __device__ __forceinline__ unsigned pk2(float lo, float hi) { const f32x2_t_ v = {lo, hi}; return __builtin_bit_cast(unsigned, __builtin_convertvector(v, bf16x2_t_)); }
; #define SG_LOAD(R, s_) do { if ((s_) < ns) { R.a0 = NTL((const GAS v4u*)(ap + (s_) * 128)); R.a1 = NTL((const GAS v4u*)(ap + (s_) * 128 + 64)); R.b0 = NTL((const GAS v4u*)(bp + (s_) * 128)); R.b1 = NTL((const GAS v4u*)(bp + (s_) * 128 + 64)); } } while (0)
; #define SG_STORE(R, b_) do { *(LAS v4u*)(As + (b_) * BUF + prow * LDT + pk) = R.a0; *(LAS v4u*)(As + (b_) * BUF + prow * LDT + pk + 64) = R.a1; *(LAS v4u*)(Bs + (b_) * BUF + prow * LDT + pk) = R.b0; *(LAS v4u*)(Bs + (b_) * BUF + prow * LDT + pk + 64) = R.b1; } while (0)
;     __device__ __forceinline__ float store4p(int row, int col, f32x4 a, const Pre& p) const {
;         const size_t o = (size_t)row * DM + col; const f32x4 v = p.s + a * alpha; *(f32x4*)(out + o) = v;
;         if (XNo) { const f32x4 gg = *(const f32x4*)(gain + col); v2u w; w.x = pk2(v[0] * gg[0], v[1] * gg[1]); w.y = pk2(v[2] * gg[2], v[3] * gg[3]); *(v2u*)(XNo + o) = w; return (v[0] * v[0] + v[1] * v[1]) + (v[2] * v[2] + v[3] * v[3]); }
;         return 0.f;
; template <class Epi>
; __device__ __forceinline__ void small_gemm(const Frame& F, const bf16* A, const bf16* Bt, int row_base, int K, const Epi E) {
;     ...
;             SG_LOAD(R3, s + 3); SG_COMP(0); if (s + 1 < ns) SG_STORE(R1, 1); LDSBAR(); if (s + 1 >= ns) break;
;             SG_LOAD(R0, s + 4); SG_COMP(1); if (s + 2 < ns) SG_STORE(R2, 0); LDSBAR(); if (s + 2 >= ns) break;
;             SG_LOAD(R1, s + 5); SG_COMP(0); if (s + 3 < ns) SG_STORE(R3, 1); LDSBAR(); if (s + 3 >= ns) break;
;             SG_LOAD(R2, s + 6); SG_COMP(1); if (s + 4 < ns) SG_STORE(R0, 0); LDSBAR();
;         }
;     ...
;         { float ss = E.store4p(r0 + 16 * (w & 3) + r, c0 + 32 * (w >> 2) + 4 * q, acc0, ep0);
;           ss += E.store4p(r0 + 16 * (w & 3) + r, c0 + 32 * (w >> 2) + 16 + 4 * q, acc1, ep1);
	ds_read_b128 v[18:21], v43 offset:52224
	s_waitcnt lgkmcnt(8)
	v_mfma_f32_16x16x32_bf16 v[14:17], v[98:101], v[102:105], v[14:17]
	ds_read_b128 v[22:25], v42 offset:17408
	ds_read_b128 v[32:35], v42 offset:17472
	ds_read_b128 v[58:61], v43 offset:52288
	v_mfma_f32_16x16x32_bf16 v[10:13], v[78:81], v[102:105], v[10:13]
	s_waitcnt lgkmcnt(9)
	v_mfma_f32_16x16x32_bf16 v[14:17], v[70:73], v[106:109], v[14:17]
	s_waitcnt lgkmcnt(8)
	v_mfma_f32_16x16x32_bf16 v[10:13], v[94:97], v[106:109], v[10:13]
	s_waitcnt lgkmcnt(2)
	v_mfma_f32_16x16x32_bf16 v[14:17], v[18:21], v[22:25], v[14:17]
	ds_read_b128 v[18:21], v43 offset:56576
	ds_read_b128 v[70:73], v43 offset:56640
	s_waitcnt lgkmcnt(1)
	v_mfma_f32_16x16x32_bf16 v[10:13], v[18:21], v[22:25], v[10:13]
	ds_read_b128 v[18:21], v43 offset:52352
	v_mfma_f32_16x16x32_bf16 v[14:17], v[58:61], v[32:35], v[14:17]
	ds_read_b128 v[22:25], v43 offset:56704
	ds_read_b128 v[58:61], v42 offset:17536
	ds_read_b128 v[78:81], v42 offset:17600
	s_waitcnt lgkmcnt(4)
	v_mfma_f32_16x16x32_bf16 v[10:13], v[70:73], v[32:35], v[10:13]
	ds_read_b128 v[32:35], v43 offset:52416
	ds_read_b128 v[70:73], v43 offset:56768
	s_waitcnt vmcnt(7)
	ds_write_b128 v41, v[62:65]
	s_waitcnt vmcnt(6)
	ds_write_b128 v41, v[66:69] offset:128
	s_waitcnt vmcnt(5)
	ds_write_b128 v41, v[90:93] offset:34816
	s_waitcnt vmcnt(4)
	ds_write_b128 v41, v[74:77] offset:34944
	s_waitcnt lgkmcnt(0)
	s_barrier
	s_waitcnt lgkmcnt(7)
	v_mfma_f32_16x16x32_bf16 v[14:17], v[18:21], v[58:61], v[14:17]
	ds_read_b128 v[18:21], v43 offset:34816
	v_mfma_f32_16x16x32_bf16 v[10:13], v[22:25], v[58:61], v[10:13]
	s_waitcnt lgkmcnt(6)
	v_mfma_f32_16x16x32_bf16 v[14:17], v[32:35], v[78:81], v[14:17]
	ds_read_b128 v[22:25], v42
	ds_read_b128 v[32:35], v42 offset:64
	ds_read_b128 v[58:61], v43 offset:34880
	s_waitcnt lgkmcnt(8)
	v_mfma_f32_16x16x32_bf16 v[10:13], v[70:73], v[78:81], v[10:13]
	s_waitcnt lgkmcnt(2)
	v_mfma_f32_16x16x32_bf16 v[14:17], v[18:21], v[22:25], v[14:17]
	ds_read_b128 v[18:21], v43 offset:39168
	ds_read_b128 v[62:65], v43 offset:39232
	s_waitcnt lgkmcnt(1)
	v_mfma_f32_16x16x32_bf16 v[10:13], v[18:21], v[22:25], v[10:13]
	ds_read_b128 v[18:21], v43 offset:34944
	v_mfma_f32_16x16x32_bf16 v[14:17], v[58:61], v[32:35], v[14:17]
	s_waitcnt lgkmcnt(1)
	v_mfma_f32_16x16x32_bf16 v[10:13], v[62:65], v[32:35], v[10:13]
	ds_read_b128 v[22:25], v42 offset:128
	ds_read_b128 v[32:35], v42 offset:192
	ds_read_b128 v[58:61], v43 offset:35008
	s_waitcnt lgkmcnt(2)
	v_mfma_f32_16x16x32_bf16 v[14:17], v[18:21], v[22:25], v[14:17]
	ds_read_b128 v[18:21], v43 offset:39296
	ds_read_b128 v[62:65], v43 offset:39360
	s_waitcnt vmcnt(3)
	ds_write_b128 v44, v[46:49] offset:17408
	s_waitcnt vmcnt(2)
	ds_write_b128 v44, v[86:89] offset:17536
	s_waitcnt vmcnt(1)
	ds_write_b128 v44, v[50:53] offset:52224
	s_waitcnt vmcnt(0)
	ds_write_b128 v44, v[54:57] offset:52352
	s_waitcnt lgkmcnt(0)
	s_waitcnt lgkmcnt(5)
	v_mfma_f32_16x16x32_bf16 v[10:13], v[18:21], v[22:25], v[10:13]
	s_barrier
	v_mfma_f32_16x16x32_bf16 v[14:17], v[58:61], v[32:35], v[14:17]
	s_waitcnt lgkmcnt(4)
	v_mfma_f32_16x16x32_bf16 v[10:13], v[62:65], v[32:35], v[10:13]
	ds_read_b128 v[18:21], v43 offset:52224
	ds_read_b128 v[22:25], v42 offset:17408
	ds_read_b128 v[32:35], v42 offset:17472
	ds_read_b128 v[46:49], v43 offset:52288
	s_waitcnt lgkmcnt(2)
	v_mfma_f32_16x16x32_bf16 v[14:17], v[18:21], v[22:25], v[14:17]
	ds_read_b128 v[18:21], v43 offset:56576
	ds_read_b128 v[50:53], v43 offset:56640
	s_waitcnt lgkmcnt(1)
	v_mfma_f32_16x16x32_bf16 v[10:13], v[18:21], v[22:25], v[10:13]
	ds_read_b128 v[18:21], v43 offset:52352
	v_mfma_f32_16x16x32_bf16 v[14:17], v[46:49], v[32:35], v[14:17]
	s_waitcnt lgkmcnt(1)
	v_mfma_f32_16x16x32_bf16 v[10:13], v[50:53], v[32:35], v[10:13]
	ds_read_b128 v[22:25], v42 offset:17536
	ds_read_b128 v[32:35], v42 offset:17600
	ds_read_b128 v[46:49], v43 offset:52416
	ds_read_b128 v[50:53], v43 offset:56768
	s_waitcnt lgkmcnt(3)
	v_mfma_f32_16x16x32_bf16 v[14:17], v[18:21], v[22:25], v[14:17]
	ds_read_b128 v[18:21], v43 offset:56704
	s_waitcnt lgkmcnt(0)
	s_barrier
	s_waitcnt lgkmcnt(0)
	v_mfma_f32_16x16x32_bf16 v[10:13], v[18:21], v[22:25], v[10:13]
	v_mfma_f32_16x16x32_bf16 v[14:17], v[46:49], v[32:35], v[14:17]
	v_mfma_f32_16x16x32_bf16 v[10:13], v[50:53], v[32:35], v[10:13]
	s_nop 6
	v_fma_f32 v8, v16, 0.5, v8
	v_fma_f32 v9, v17, 0.5, v9
	v_pk_fma_f32 v[6:7], v[14:15], 0.5, v[6:7] op_sel_hi:[1,0,1]
	v_pk_fma_f32 v[4:5], v[12:13], 0.5, v[4:5] op_sel_hi:[1,0,1]
	v_pk_fma_f32 v[2:3], v[10:11], 0.5, v[2:3] op_sel_hi:[1,0,1]
	global_store_dwordx4 v[30:31], v[6:9], off
	global_store_dwordx4 v[30:31], v[2:5], off offset:64
	s_cbranch_scc1 .LBB0_1876

; #define LAS __attribute__((address_space(3)))
; template <class Epi>
; __device__ __forceinline__ void small_gemm(const Frame& F, const bf16* A, const bf16* Bt, int row_base, int K, const Epi E) {
;     constexpr int LDT = 136, BUF = 64 * LDT;
;     LAS bf16* As = (LAS bf16*)F.lds; LAS bf16* Bs = As + 2 * BUF;
;     const int tid = F.tid, lane = F.lane, w = F.wave, r = lane & 15, q = lane >> 4, prow = tid >> 3, pk = (tid & 7) * 8, ns = K / 128;
;     for (int u = F.vcu; u < 256; u += F.G) {
;         const int r0 = row_base + (u >> 4) * 64, c0 = (u & 15) * 64;
;         const bf16* ap = A + (size_t)(r0 + prow) * K + pk; const bf16* bp = Bt + (size_t)(c0 + prow) * K + pk;
.LBB0_1935:
	v_mov_b32_e32 v2, v0
	s_cmp_eq_u32 s33, s33
	v_readfirstlane_b32 s2, v2
	s_cbranch_scc1 .LBB0_1938
	v_lshlrev_b32_e32 v3, 4, v2
	s_lshr_b32 s3, s2, 2
	s_ashr_i32 s2, s2, 3
	v_ashrrev_i32_e32 v1, 3, v2
	v_and_b32_e32 v4, 0x70, v3
	v_bfe_u32 v3, v2, 4, 2
	v_and_b32_e32 v2, 15, v2
	s_andn2_b32 s2, s2, 31
	v_mov_b32_e32 v5, 0
	v_and_or_b32 v38, s3, 48, v2
	s_movk_i32 s3, 0x110
	v_or_b32_e32 v2, s2, v2
	v_lshl_add_u64 v[26:27], s[28:29], 0, v[4:5]
	v_lshl_add_u64 v[28:29], s[10:11], 0, v[4:5]
	v_lshlrev_b32_e32 v39, 2, v3
	v_mul_lo_u32 v5, v1, s3
	v_mul_u32_u24_e32 v6, 0x110, v38
	v_lshlrev_b32_e32 v3, 4, v3
	v_mul_lo_u32 v2, v2, s3
	v_add3_u32 v40, 0, v4, v5
	v_add3_u32 v41, 0, v6, v3
	v_add3_u32 v42, 0, v2, v3
	v_add3_u32 v43, 0, v5, v4
	s_lshl_b32 s3, s33, 6
	s_lshl_b32 s6, s18, 6
	s_lshl_b32 s7, s33, 2
	s_lshl_b32 s8, s18, 2
	s_movk_i32 s9, 0x1600
	s_movk_i32 s10, 0x1000
	s_mov_b32 s11, s33
